# MoBA/memory attention: SiLU-gate row DMA issued after the unit start-up wait (loads under the first tile), first loop-top wait skipped
# speedup vs baseline: 1.0115x; 1.0014x over previous
.LBB0_272:
	s_or_b64 exec, exec, s[0:1]
	s_xor_b64 s[0:1], s[22:23], -1
	s_cmpk_gt_i32 s89, 0xbf
	s_mov_b64 s[52:53], -1
	s_cbranch_scc0 .LBB0_438
	s_cmpk_gt_u32 s89, 0x17f
	s_cbranch_scc0 .LBB0_401
	s_cmpk_gt_u32 s89, 0x47f
	s_cbranch_scc0 .LBB0_317
	s_cmpk_gt_u32 s89, 0x67f
	s_mov_b64 s[2:3], -1
	s_cbranch_scc0 .LBB0_305
	s_add_i32 s2, s89, 0xfffff980
	s_lshr_b32 s2, s2, 6
	v_mov_b32_e32 v2, v175
	s_bfe_u32 s56, s89, 0x30003
	s_sub_i32 s94, 1, s2
	s_lshl_b32 s20, s94, 8
	v_readfirstlane_b32 s2, v2
	s_ashr_i32 s58, s2, 6
	s_lshl_b32 s2, s56, 11
	s_or_b32 s54, s20, s2
	s_mul_i32 s2, s54, 0x5800
	s_add_u32 s2, s6, s2
	s_addc_u32 s3, s7, 0
	s_lshl_b32 s52, s89, 7
	s_and_b32 s57, s52, 0x380
	s_lshl_b32 s90, s57, 1
	s_add_u32 s2, s2, s90
	s_addc_u32 s3, s3, 0
	s_mul_i32 s52, s56, 0x2c00000
	s_add_u32 s52, s6, s52
	v_and_b32_e32 v11, 31, v2
	s_addc_u32 s53, s7, 0
	s_lshl_b32 s66, s58, 5
	v_or_b32_e32 v172, s66, v11
	v_mov_b64_e32 v[4:5], s[2:3]
	s_add_u32 s52, s52, s90
	v_mad_i64_i32 v[4:5], s[2:3], v172, s62, v[4:5]
	s_addc_u32 s53, s53, 0
	s_add_u32 s2, s52, 0x1000
	s_addc_u32 s3, s53, 0
	s_lshl_b32 s55, s58, 13
	s_add_i32 s59, s55, 0
	s_add_i32 s91, s59, 0x10000
	s_ashr_i32 s55, s66, 31
	s_add_u32 s92, s54, s66
	s_addc_u32 s93, 0, s55
	s_mul_i32 s54, s93, 0x5800
	s_mul_hi_u32 s55, s92, 0x5800
	s_add_i32 s55, s55, s54
	s_mul_i32 s54, s92, 0x5800
	s_add_u32 s54, s6, s54
	s_addc_u32 s55, s7, s55
	s_add_u32 s54, s54, s90
	v_bfe_u32 v10, v2, 5, 1
	s_addc_u32 s55, s55, 0
	v_lshlrev_b32_e32 v0, 4, v10
	s_add_u32 s54, s54, 0x1800
	v_bfe_u32 v170, v2, 4, 2
	v_lshl_add_u64 v[4:5], v[4:5], 0, v[0:1]
	s_addc_u32 s55, s55, 0
	v_xor_b32_e32 v3, v170, v2
	v_mul_u32_u24_e32 v0, 0x5800, v170
	global_load_dwordx4 v[112:115], v[4:5], off
	global_load_dwordx4 v[116:119], v[4:5], off offset:32
	global_load_dwordx4 v[120:123], v[4:5], off offset:64
	global_load_dwordx4 v[124:127], v[4:5], off offset:96
	global_load_dwordx4 v[128:131], v[4:5], off offset:128
	global_load_dwordx4 v[132:135], v[4:5], off offset:160
	global_load_dwordx4 v[136:139], v[4:5], off offset:192
	global_load_dwordx4 v[140:143], v[4:5], off offset:224
	v_lshl_add_u64 v[4:5], s[54:55], 0, v[0:1]
	v_lshlrev_b32_e32 v0, 3, v3
	v_and_b32_e32 v0, 0x78, v0
	v_lshlrev_b32_e32 v144, 1, v0
	v_mov_b32_e32 v145, v1
	v_lshl_add_u64 v[4:5], v[4:5], 0, v[144:145]
	s_mov_b32 m0, s91
	v_bitop3_b32 v3, v170, v2, 4 bitop3:0x36
	v_mad_u32_u24 v0, v170, s62, v188
	s_nop 0
	v_lshl_add_u64 v[4:5], s[54:55], 0, v[0:1]
	v_lshlrev_b32_e32 v0, 3, v3
	v_and_b32_e32 v0, 0x78, v0
	v_lshlrev_b32_e32 v146, 1, v0
	v_mov_b32_e32 v147, v1
	v_lshl_add_u64 v[4:5], v[4:5], 0, v[146:147]
	s_add_i32 m0, s59, 0x10400
	v_bitop3_b32 v3, v170, v2, 8 bitop3:0x36
	v_mad_u32_u24 v0, v170, s62, v189
	s_nop 0
	v_lshl_add_u64 v[4:5], s[54:55], 0, v[0:1]
	v_lshlrev_b32_e32 v0, 3, v3
	v_and_b32_e32 v0, 0x78, v0
	v_lshlrev_b32_e32 v148, 1, v0
	v_mov_b32_e32 v149, v1
	v_lshl_add_u64 v[4:5], v[4:5], 0, v[148:149]
	s_add_i32 m0, s59, 0x10800
	v_bitop3_b32 v3, v170, v2, 12 bitop3:0x36
	v_mad_u32_u24 v0, v170, s62, v190
	s_nop 0
	v_lshl_add_u64 v[4:5], s[54:55], 0, v[0:1]
	v_lshlrev_b32_e32 v0, 3, v3
	v_and_b32_e32 v0, 0x78, v0
	v_lshlrev_b32_e32 v152, 1, v0
	v_mov_b32_e32 v153, v1
	v_lshl_add_u64 v[4:5], v[4:5], 0, v[152:153]
	s_add_i32 m0, s59, 0x10c00
	v_mad_u32_u24 v0, v170, s62, v191
	s_nop 0
	v_lshl_add_u64 v[4:5], s[54:55], 0, v[0:1]
	v_lshl_add_u64 v[4:5], v[4:5], 0, v[144:145]
	s_add_i32 m0, s59, 0x11000
	v_bitop3_b32 v3, v170, v2, 20 bitop3:0x36
	v_mad_u32_u24 v0, v170, s62, v192
	s_nop 0
	v_lshl_add_u64 v[4:5], s[54:55], 0, v[0:1]
	v_lshlrev_b32_e32 v0, 3, v3
	v_and_b32_e32 v0, 0x78, v0
	v_lshlrev_b32_e32 v150, 1, v0
	v_mov_b32_e32 v151, v1
	v_lshl_add_u64 v[4:5], v[4:5], 0, v[150:151]
	s_add_i32 m0, s59, 0x11400
	v_bitop3_b32 v3, v170, v2, 24 bitop3:0x36
	v_mad_u32_u24 v0, v170, s62, v193
	s_nop 0
	v_lshl_add_u64 v[4:5], s[54:55], 0, v[0:1]
	v_lshlrev_b32_e32 v0, 3, v3
	v_and_b32_e32 v0, 0x78, v0
	v_lshlrev_b32_e32 v154, 1, v0
	v_mov_b32_e32 v155, v1
	v_lshl_add_u64 v[4:5], v[4:5], 0, v[154:155]
	s_add_i32 m0, s59, 0x11800
	v_bitop3_b32 v3, v170, v2, 28 bitop3:0x36
	v_mad_u32_u24 v0, v170, s62, v194
	s_nop 0
	v_lshl_add_u64 v[4:5], s[54:55], 0, v[0:1]
	v_lshlrev_b32_e32 v0, 3, v3
	v_and_b32_e32 v0, 0x78, v0
	s_lshl_b32 s54, s58, 3
	v_lshlrev_b32_e32 v156, 1, v0
	v_mov_b32_e32 v157, v1
	v_or_b32_e32 v158, s54, v170
	v_lshl_add_u64 v[4:5], v[4:5], 0, v[156:157]
	s_add_i32 m0, s59, 0x11c00
	s_lshl_b32 s95, s58, 11
	v_bitop3_b32 v0, s54, v2, v170 bitop3:0x36
	s_lshl_b32 s58, s58, 1
	v_ashrrev_i32_e32 v159, 31, v158
	s_nop 0
	v_and_b32_e32 v145, 15, v2
	v_lshlrev_b32_e32 v3, 2, v170
	s_and_b32 s54, s58, 2
	v_lshl_add_u64 v[4:5], v[158:159], 0, s[20:21]
	v_mov_b64_e32 v[6:7], s[52:53]
	v_lshlrev_b32_e32 v0, 3, v0
	v_bitop3_b32 v12, s54, v145, v3 bitop3:0x36
	v_mad_u64_u32 v[8:9], s[54:55], v4, s62, v[6:7]
	v_and_b32_e32 v0, 0x78, v0
	v_mad_i32_i24 v9, v5, s62, v9
	v_lshlrev_b32_e32 v0, 1, v0
	v_lshl_add_u64 v[8:9], v[8:9], 0, v[0:1]
	s_add_i32 s59, s95, 0
	v_lshl_add_u64 v[8:9], v[8:9], 0, s[24:25]
	s_mov_b32 m0, s59
	s_or_b32 s58, s58, 1
	global_load_lds_dwordx4 v[8:9], off
	v_mov_b64_e32 v[8:9], s[2:3]
	v_mad_u64_u32 v[14:15], s[54:55], v4, s62, v[8:9]
	v_mad_i32_i24 v15, v5, s62, v15
	v_lshlrev_b32_e32 v4, 4, v12
	v_mov_b32_e32 v5, v1
	s_lshl_b32 s54, s58, 2
	v_lshl_add_u64 v[4:5], v[14:15], 0, v[4:5]
	s_add_i32 m0, s59, 0x8000
	v_or_b32_e32 v160, s54, v170
	global_load_lds_dwordx4 v[4:5], off
	v_bitop3_b32 v4, s54, v2, v170 bitop3:0x36
	s_and_b32 s54, s58, 3
	v_ashrrev_i32_e32 v161, 31, v160
	v_bitop3_b32 v13, s54, v145, v3 bitop3:0x36
	v_lshl_add_u64 v[14:15], v[160:161], 0, s[20:21]
	v_lshlrev_b32_e32 v3, 3, v4
	v_mad_u64_u32 v[6:7], s[54:55], v14, s62, v[6:7]
	v_and_b32_e32 v3, 0x78, v3
	v_mad_i32_i24 v7, v15, s62, v7
	v_lshlrev_b32_e32 v4, 1, v3
	v_mov_b32_e32 v5, v1
	s_lshl_b32 s96, s58, 10
	v_lshl_add_u64 v[6:7], v[6:7], 0, v[4:5]
	s_add_i32 s58, s96, 0
	v_lshl_add_u64 v[6:7], v[6:7], 0, s[24:25]
	s_mov_b32 m0, s58
	s_lshl_b32 s75, s94, 7
	global_load_lds_dwordx4 v[6:7], off
	v_mad_u64_u32 v[6:7], s[54:55], v14, s62, v[8:9]
	v_mad_i32_i24 v7, v15, s62, v7
	v_lshlrev_b32_e32 v8, 4, v13
	v_mov_b32_e32 v9, v1
	v_lshl_add_u64 v[6:7], v[6:7], 0, v[8:9]
	s_add_i32 m0, s58, 0x8000
	v_cmp_gt_i32_e32 vcc, s75, v2
	global_load_lds_dwordx4 v[6:7], off
	s_and_saveexec_b64 s[54:55], vcc
	s_cbranch_execz .LBB0_289
	v_and_b32_e32 v3, 0x7f, v2
	s_lshl_b32 s76, s56, 3
	s_lshl_b32 s56, s57, 2
	v_lshlrev_b32_e32 v6, 2, v3
	v_add_u32_e32 v3, 0x200, v2
	s_add_u32 s56, s77, s56
	v_max_i32_e32 v8, s75, v3
	s_addc_u32 s57, s78, 0
	v_mov_b32_e32 v7, v1
	v_xad_u32 v9, v2, -1, v8
	v_lshl_add_u64 v[6:7], s[56:57], 0, v[6:7]
	v_cmp_lt_u32_e32 vcc, s63, v9
	s_mov_b64 s[58:59], -1
	v_mov_b32_e32 v8, v2
	s_and_saveexec_b64 s[56:57], vcc
	s_cbranch_execz .LBB0_286
	v_lshrrev_b32_e32 v14, 9, v9
	v_add_u32_e32 v8, -1, v14
	v_lshrrev_b32_e32 v9, 1, v8
	v_add_u32_e32 v15, 1, v9
	v_cmp_lt_u32_e32 vcc, 5, v8
	v_mov_b32_e32 v18, 0
	v_mov_b64_e32 v[8:9], v[2:3]
	s_and_saveexec_b64 s[58:59], vcc
	s_cbranch_execz .LBB0_282
	v_and_b32_e32 v16, -4, v15
	v_lshl_add_u32 v17, v2, 2, s64
	s_mov_b32 s97, 0
	s_mov_b64 s[60:61], 0
	v_mov_b64_e32 v[8:9], v[2:3]

.LBB0_289:
	s_or_b64 exec, exec, s[54:55]
	v_lshlrev_b32_e32 v3, 3, v13
	v_lshl_add_u64 v[162:163], s[52:53], 0, v[0:1]
	v_lshlrev_b32_e32 v0, 1, v3
	v_and_b32_e32 v174, 63, v2
	v_lshl_add_u64 v[168:169], s[2:3], 0, v[0:1]
	v_lshlrev_b32_e32 v179, 2, v10
	v_bfe_u32 v0, v2, 2, 2
	v_lshrrev_b32_e32 v3, 3, v2
	v_bfe_u32 v2, v2, 1, 1
	v_lshl_add_u64 v[166:167], s[52:53], 0, v[4:5]
	v_and_or_b32 v2, v3, 2, v2
	v_lshlrev_b32_e32 v3, 2, v0
	v_lshlrev_b32_e32 v5, 3, v174
	v_or_b32_e32 v0, v179, v0
	v_or_b32_e32 v4, v3, v10
	v_and_b32_e32 v180, 8, v5
	v_xor_b32_e32 v5, v10, v145
	v_lshlrev_b32_e32 v202, 8, v0
	v_bitop3_b32 v0, v3, v2, v10 bitop3:0x36
	v_lshlrev_b32_e32 v181, 4, v5
	v_bitop3_b32 v5, v10, v145, 2 bitop3:0x36
	v_lshlrev_b32_e32 v203, 4, v0
	v_bitop3_b32 v0, v4, v2, 2 bitop3:0x36
	v_lshlrev_b32_e32 v182, 4, v5
	v_bitop3_b32 v5, v10, v145, 4 bitop3:0x36
	v_lshlrev_b32_e32 v204, 4, v0
	v_or_b32_e32 v0, 4, v2
	v_lshlrev_b32_e32 v183, 4, v5
	v_bitop3_b32 v5, v10, v145, 6 bitop3:0x36
	v_bitop3_b32 v0, v4, v0, 2 bitop3:0x36
	v_lshlrev_b32_e32 v184, 4, v5
	v_bitop3_b32 v5, v10, v145, 8 bitop3:0x36
	v_lshlrev_b32_e32 v206, 4, v0
	v_or_b32_e32 v0, 8, v2
	v_lshlrev_b32_e32 v185, 4, v5
	v_bitop3_b32 v5, v10, v145, 10 bitop3:0x36
	v_bitop3_b32 v0, v4, v0, 2 bitop3:0x36
	v_lshlrev_b32_e32 v186, 4, v5
	v_bitop3_b32 v5, v10, v145, 12 bitop3:0x36
	v_bitop3_b32 v3, v2, v4, 4 bitop3:0x36
	v_lshlrev_b32_e32 v208, 4, v0
	v_or_b32_e32 v0, 12, v2
	v_lshlrev_b32_e32 v6, 3, v12
	v_mov_b32_e32 v7, v1
	v_lshlrev_b32_e32 v200, 4, v5
	v_bitop3_b32 v5, v10, v145, 14 bitop3:0x36
	v_lshlrev_b32_e32 v205, 4, v3
	v_bitop3_b32 v3, v2, v4, 8 bitop3:0x36
	v_bitop3_b32 v2, v2, v4, 12 bitop3:0x36
	v_bitop3_b32 v0, v4, v0, 2 bitop3:0x36
	v_mov_b32_e32 v14, v1
	v_mov_b32_e32 v15, v1
	v_lshlrev_b32_e32 v176, 3, v10
	s_lshl_b32 s56, s94, 2
	v_lshl_add_u64 v[164:165], v[6:7], 1, s[2:3]
	v_lshlrev_b32_e32 v177, 8, v11
	v_lshlrev_b32_e32 v201, 4, v5
	v_lshlrev_b32_e32 v207, 4, v3
	v_lshlrev_b32_e32 v209, 4, v2
	v_lshlrev_b32_e32 v210, 4, v0
	v_mov_b32_e32 v0, v1
	v_mov_b32_e32 v2, v1
	v_mov_b32_e32 v3, v1
	v_mov_b32_e32 v4, v1
	v_mov_b32_e32 v5, v1
	v_mov_b32_e32 v6, v1
	v_mov_b32_e32 v8, v1
	v_mov_b32_e32 v9, v1
	v_mov_b32_e32 v10, v1
	v_mov_b32_e32 v11, v1
	v_mov_b32_e32 v12, v1
	v_mov_b32_e32 v13, v1
	v_mov_b64_e32 v[30:31], v[14:15]
	v_mov_b64_e32 v[46:47], v[14:15]
	v_mov_b64_e32 v[62:63], v[14:15]
	v_mov_b64_e32 v[78:79], v[14:15]
	v_or_b32_e32 v147, 4, v170
	v_or_b32_e32 v149, 8, v170
	v_or_b32_e32 v153, 12, v170
	v_or_b32_e32 v151, 20, v170
	v_or_b32_e32 v155, 24, v170
	v_or_b32_e32 v157, 28, v170
	s_add_i32 s56, s56, 4
	s_or_b32 s57, s66, 31
	v_add_u32_e32 v178, 0, v177
	s_mov_b32 s58, 0
	v_mov_b32_e32 v211, 0
	v_mov_b32_e32 v212, 0xf149f2ca
	s_mov_b32 s59, 0
	v_mov_b64_e32 v[28:29], v[12:13]
	v_mov_b64_e32 v[26:27], v[10:11]
	v_mov_b64_e32 v[24:25], v[8:9]
	v_mov_b64_e32 v[22:23], v[6:7]
	v_mov_b64_e32 v[20:21], v[4:5]
	v_mov_b64_e32 v[18:19], v[2:3]
	v_mov_b64_e32 v[16:17], v[0:1]
	v_mov_b64_e32 v[44:45], v[12:13]
	v_mov_b64_e32 v[42:43], v[10:11]
	v_mov_b64_e32 v[40:41], v[8:9]
	v_mov_b64_e32 v[38:39], v[6:7]
	v_mov_b64_e32 v[36:37], v[4:5]
	v_mov_b64_e32 v[34:35], v[2:3]
	v_mov_b64_e32 v[32:33], v[0:1]
	v_mov_b64_e32 v[60:61], v[12:13]
	v_mov_b64_e32 v[58:59], v[10:11]
	v_mov_b64_e32 v[56:57], v[8:9]
	v_mov_b64_e32 v[54:55], v[6:7]
	v_mov_b64_e32 v[52:53], v[4:5]
	v_mov_b64_e32 v[50:51], v[2:3]
	v_mov_b64_e32 v[48:49], v[0:1]
	v_mov_b64_e32 v[76:77], v[12:13]
	v_mov_b64_e32 v[74:75], v[10:11]
	v_mov_b64_e32 v[72:73], v[8:9]
	v_mov_b64_e32 v[70:71], v[6:7]
	v_mov_b64_e32 v[68:69], v[4:5]
	v_mov_b64_e32 v[66:67], v[2:3]
	v_mov_b64_e32 v[64:65], v[0:1]
	s_mov_b32 s52, 0
	s_waitcnt vmcnt(0) lgkmcnt(0)
	s_barrier
	ds_read_b32 v246, v173
	s_waitcnt lgkmcnt(0)
	v_cmp_gt_u32_e32 vcc, 0x180, v246
	s_nop 1
	v_cndmask_b32_e64 v252, 0, 1, vcc
	v_cmp_gt_u32_e32 vcc, 0xc0, v246
	s_nop 1
	v_cndmask_b32_e64 v253, 0, 1, vcc
	v_mul_u32_u24_e32 v255, 0x5c0, v252
	v_mul_u32_u24_e32 v247, 0xc0, v253
	v_add_u32_e32 v255, v255, v247
	v_sub_u32_e32 v255, 0x680, v255
	v_sub_u32_e32 v255, v246, v255
	v_add_u32_e32 v252, v252, v253
	v_mad_u32_u24 v252, v252, 3, 1
	v_lshrrev_b32_e32 v253, 6, v255
	v_sub_u32_e32 v252, v252, v253
	v_bfe_u32 v247, v255, 3, 3
	v_lshlrev_b32_e32 v247, 11, v247
	v_lshl_add_u32 v247, v252, 8, v247
	v_and_b32_e32 v253, 7, v255
	v_lshlrev_b32_e32 v248, 8, v253
	v_mov_b32_e32 v249, 0x1800
	v_mov_b32_e32 v250, v247
	v_add_u32_e32 v251, 0x800, v248
	v_subrev_u32_e32 v255, 0x180, v246
	v_cmp_gt_u32_e32 vcc, 0x300, v255
	s_nop 3
	s_mov_b64 s[98:99], vcc
	v_bfe_u32 v246, v255, 5, 3
	v_lshlrev_b32_e32 v246, 11, v246
	v_and_b32_e32 v253, 7, v255
	v_lshl_add_u32 v252, v253, 8, v246
	v_cndmask_b32_e64 v247, v247, v252, s[98:99]
	v_lshlrev_b32_e32 v252, 8, v253
	v_and_b32_e32 v253, 0xfffffe00, v252
	v_cmp_le_u32_e32 vcc, 0x200, v255
	s_nop 1
	v_cndmask_b32_e32 v253, v253, v252, vcc
	v_cmp_le_u32_e32 vcc, 0x100, v255
	s_nop 1
	v_cndmask_b32_e64 v253, 0, v253, vcc
	v_subrev_u32_e32 v252, 0x80, v252
	v_max_i32_e32 v252, v252, v253
	v_add_u32_e32 v252, v252, v246
	v_cndmask_b32_e64 v250, v250, v252, s[98:99]
	v_lshrrev_b32_e32 v252, 8, v255
	v_bfe_u32 v253, v255, 3, 2
	v_lshl_add_u32 v252, v252, 2, v253
	v_lshlrev_b32_e32 v252, 8, v252
	v_add_u32_e32 v253, 0x2000, v252
	v_cndmask_b32_e64 v248, v248, v253, s[98:99]
	v_add_u32_e32 v253, 0x2c00, v252
	v_cndmask_b32_e64 v251, v251, v253, s[98:99]
	v_cndmask_b32_e64 v249, v249, 0, s[98:99]
	v_subrev_u32_e32 v255, 0x300, v255
	v_cmp_gt_u32_e32 vcc, 0x200, v255
	s_nop 3
	s_mov_b64 s[100:101], vcc
	v_lshrrev_b32_e32 v252, 6, v255
	v_lshlrev_b32_e32 v252, 11, v252
	v_bfe_u32 v253, v255, 1, 3
	v_lshl_add_u32 v252, v253, 8, v252
	v_cndmask_b32_e64 v247, v247, v252, s[100:101]
	v_cndmask_b32_e64 v250, v250, v252, s[100:101]
	v_bfe_u32 v252, v255, 4, 2
	v_lshlrev_b32_e32 v252, 9, v252
	v_add_u32_e32 v252, 0x4800, v252
	v_cndmask_b32_e64 v248, v248, v252, s[100:101]
	v_add_u32_e32 v253, 0x100, v252
	v_cndmask_b32_e64 v251, v251, v253, s[100:101]
	v_and_b32_e32 v252, 1, v255
	v_lshlrev_b32_e32 v252, 8, v252
	v_add_u32_e32 v252, 0x800, v252
	v_cndmask_b32_e64 v249, v249, v252, s[100:101]
	v_lshrrev_b32_e32 v252, 6, v175
	v_lshlrev_b32_e32 v252, 5, v252
	v_bfe_u32 v253, v175, 4, 2
	v_add3_u32 v247, v247, v252, v253
	v_mul_u32_u24_e32 v247, 0x5800, v247
	v_add3_u32 v247, v247, v248, v249
	v_and_b32_e32 v252, 15, v175
	v_add_u32_e32 v248, 0, v253
	v_xor_b32_e32 v248, v252, v248
	v_lshlrev_b32_e32 v248, 4, v248
	v_add_u32_e32 v249, 4, v253
	v_xor_b32_e32 v249, v252, v249
	v_lshlrev_b32_e32 v249, 4, v249
	v_add_u32_e32 v250, 8, v253
	v_xor_b32_e32 v250, v252, v250
	v_lshlrev_b32_e32 v250, 4, v250
	v_add_u32_e32 v251, 12, v253
	v_xor_b32_e32 v251, v252, v251
	v_lshlrev_b32_e32 v251, 4, v251
	v_readfirstlane_b32 s98, v175
	s_add_u32 s100, s38, 0xba00000
	s_addc_u32 s101, s39, 0
	s_lshr_b32 s98, s98, 6
	s_lshl_b32 s98, s98, 13
	s_add_i32 s98, s98, 0x10000
	v_add_u32_e32 v254, v247, v248
	v_mov_b32_e32 v255, 0
	v_lshl_add_u64 v[254:255], s[100:101], 0, v[254:255]
	s_add_i32 m0, s98, 0x0
	v_add_u32_e32 v247, 0x16000, v247
	global_load_lds_dwordx4 v[254:255], off
	v_add_u32_e32 v254, v247, v249
	v_mov_b32_e32 v255, 0
	v_lshl_add_u64 v[254:255], s[100:101], 0, v[254:255]
	s_add_i32 m0, s98, 0x400
	v_add_u32_e32 v247, 0x16000, v247
	global_load_lds_dwordx4 v[254:255], off
	v_add_u32_e32 v254, v247, v250
	v_mov_b32_e32 v255, 0
	v_lshl_add_u64 v[254:255], s[100:101], 0, v[254:255]
	s_add_i32 m0, s98, 0x800
	v_add_u32_e32 v247, 0x16000, v247
	global_load_lds_dwordx4 v[254:255], off
	v_add_u32_e32 v254, v247, v251
	v_mov_b32_e32 v255, 0
	v_lshl_add_u64 v[254:255], s[100:101], 0, v[254:255]
	s_add_i32 m0, s98, 0xc00
	v_add_u32_e32 v247, 0x16000, v247
	global_load_lds_dwordx4 v[254:255], off
	v_add_u32_e32 v254, v247, v248
	v_mov_b32_e32 v255, 0
	v_lshl_add_u64 v[254:255], s[100:101], 0, v[254:255]
	s_add_i32 m0, s98, 0x1000
	v_add_u32_e32 v247, 0x16000, v247
	global_load_lds_dwordx4 v[254:255], off
	v_add_u32_e32 v254, v247, v249
	v_mov_b32_e32 v255, 0
	v_lshl_add_u64 v[254:255], s[100:101], 0, v[254:255]
	s_add_i32 m0, s98, 0x1400
	v_add_u32_e32 v247, 0x16000, v247
	global_load_lds_dwordx4 v[254:255], off
	v_add_u32_e32 v254, v247, v250
	v_mov_b32_e32 v255, 0
	v_lshl_add_u64 v[254:255], s[100:101], 0, v[254:255]
	s_add_i32 m0, s98, 0x1800
	v_add_u32_e32 v247, 0x16000, v247
	global_load_lds_dwordx4 v[254:255], off
	v_add_u32_e32 v254, v247, v251
	v_mov_b32_e32 v255, 0
	v_lshl_add_u64 v[254:255], s[100:101], 0, v[254:255]
	s_add_i32 m0, s98, 0x1c00
	s_nop 0
	global_load_lds_dwordx4 v[254:255], off
	s_branch .Lzd_entry_0

.Lzd_entry_0:
	s_add_i32 s60, s52, 1
	s_cmp_ge_u32 s60, s56
	s_barrier
	s_cbranch_scc1 .LBB0_294
	s_cmp_lt_u32 s52, 3
	s_cselect_b32 s2, s20, 0xffffff00
	s_add_i32 s2, s2, s59
	s_add_i32 s2, s2, 64
	s_ashr_i32 s3, s2, 31
	s_add_i32 s53, s58, 0x4000
	s_and_b32 s53, s53, 0x4000
	v_lshl_add_u64 v[2:3], s[2:3], 0, v[158:159]
	v_mad_u64_u32 v[4:5], s[54:55], v2, s62, v[162:163]
	s_add_i32 s53, s53, 0
	v_mad_i32_i24 v5, v3, s62, v5
	s_add_i32 s61, s53, s95
	v_lshl_add_u64 v[4:5], v[4:5], 0, s[24:25]
	s_mov_b32 m0, s61
	s_add_i32 s53, s53, s96
	global_load_lds_dwordx4 v[4:5], off
	v_mad_u64_u32 v[4:5], s[54:55], v2, s62, v[164:165]
	v_mad_i32_i24 v5, v3, s62, v5
	s_add_i32 m0, s61, 0x8000
	v_lshl_add_u64 v[2:3], s[2:3], 0, v[160:161]
	global_load_lds_dwordx4 v[4:5], off
	v_mad_u64_u32 v[4:5], s[2:3], v2, s62, v[166:167]
	v_mad_i32_i24 v5, v3, s62, v5
	v_lshl_add_u64 v[4:5], v[4:5], 0, s[24:25]
	s_mov_b32 m0, s53
	s_nop 0
	global_load_lds_dwordx4 v[4:5], off
	v_mad_u64_u32 v[4:5], s[2:3], v2, s62, v[168:169]
	v_mad_i32_i24 v5, v3, s62, v5
	s_add_i32 m0, s53, 0x8000
	s_nop 0
	global_load_lds_dwordx4 v[4:5], off

.LBB0_401:
	s_andn2_b64 vcc, exec, s[52:53]
	s_cbranch_vccnz .LBB0_437
	s_add_i32 s66, s89, 0xffffff40
	s_lshr_b32 s0, s66, 6
	v_mov_b32_e32 v2, v175
	s_bfe_u32 s2, s89, 0x30003
	s_sub_i32 s94, 4, s0
	s_lshl_b32 s20, s94, 8
	v_readfirstlane_b32 s0, v2
	s_ashr_i32 s56, s0, 6
	s_lshl_b32 s0, s2, 11
	s_or_b32 s57, s20, s0
	s_mul_i32 s0, s57, 0x5800
	s_add_u32 s0, s6, s0
	s_addc_u32 s1, s7, 0
	s_lshl_b32 s3, s89, 7
	s_and_b32 s3, s3, 0x380
	s_lshl_b32 s60, s3, 1
	s_add_u32 s0, s0, s60
	s_addc_u32 s1, s1, 0
	s_mul_i32 s52, s2, 0x2c00000
	s_add_u32 s52, s6, s52
	s_addc_u32 s53, s7, 0
	s_lshl_b32 s95, s56, 5
	v_and_b32_e32 v73, 31, v2
	s_add_u32 s54, s52, s60
	v_or_b32_e32 v172, s95, v73
	v_mov_b64_e32 v[4:5], s[0:1]
	s_addc_u32 s55, s53, 0
	v_mad_i64_i32 v[4:5], s[0:1], v172, s62, v[4:5]
	s_add_u32 s52, s54, 0x1000
	s_addc_u32 s53, s55, 0
	s_lshl_b32 s0, s56, 13
	s_add_i32 s58, s0, 0
	s_add_i32 s61, s58, 0x10000
	s_ashr_i32 s0, s95, 31
	s_add_u32 s90, s57, s95
	s_addc_u32 s91, 0, s0
	s_mul_i32 s0, s91, 0x5800
	s_mul_hi_u32 s1, s90, 0x5800
	s_add_i32 s1, s1, s0
	s_mul_i32 s0, s90, 0x5800
	s_add_u32 s0, s6, s0
	s_addc_u32 s1, s7, s1
	s_add_u32 s0, s0, s60
	v_bfe_u32 v72, v2, 5, 1
	s_addc_u32 s1, s1, 0
	v_lshlrev_b32_e32 v0, 4, v72
	s_add_u32 s0, s0, 0x1800
	v_bfe_u32 v170, v2, 4, 2
	v_lshl_add_u64 v[4:5], v[4:5], 0, v[0:1]
	s_addc_u32 s1, s1, 0
	v_xor_b32_e32 v3, v170, v2
	v_mul_u32_u24_e32 v0, 0x5800, v170
	global_load_dwordx4 v[112:115], v[4:5], off
	global_load_dwordx4 v[116:119], v[4:5], off offset:32
	global_load_dwordx4 v[120:123], v[4:5], off offset:64
	global_load_dwordx4 v[124:127], v[4:5], off offset:96
	global_load_dwordx4 v[128:131], v[4:5], off offset:128
	global_load_dwordx4 v[132:135], v[4:5], off offset:160
	global_load_dwordx4 v[136:139], v[4:5], off offset:192
	global_load_dwordx4 v[140:143], v[4:5], off offset:224
	v_lshl_add_u64 v[4:5], s[0:1], 0, v[0:1]
	v_lshlrev_b32_e32 v0, 3, v3
	v_and_b32_e32 v0, 0x78, v0
	v_lshlrev_b32_e32 v144, 1, v0
	v_mov_b32_e32 v145, v1
	v_lshl_add_u64 v[4:5], v[4:5], 0, v[144:145]
	s_mov_b32 m0, s61
	v_bitop3_b32 v3, v170, v2, 4 bitop3:0x36
	v_mad_u32_u24 v0, v170, s62, v188
	s_nop 0
	v_lshl_add_u64 v[4:5], s[0:1], 0, v[0:1]
	v_lshlrev_b32_e32 v0, 3, v3
	v_and_b32_e32 v0, 0x78, v0
	v_lshlrev_b32_e32 v146, 1, v0
	v_mov_b32_e32 v147, v1
	v_lshl_add_u64 v[4:5], v[4:5], 0, v[146:147]
	s_add_i32 m0, s58, 0x10400
	v_bitop3_b32 v3, v170, v2, 8 bitop3:0x36
	v_mad_u32_u24 v0, v170, s62, v189
	s_nop 0
	v_lshl_add_u64 v[4:5], s[0:1], 0, v[0:1]
	v_lshlrev_b32_e32 v0, 3, v3
	v_and_b32_e32 v0, 0x78, v0
	v_lshlrev_b32_e32 v148, 1, v0
	v_mov_b32_e32 v149, v1
	v_lshl_add_u64 v[4:5], v[4:5], 0, v[148:149]
	s_add_i32 m0, s58, 0x10800
	v_bitop3_b32 v3, v170, v2, 12 bitop3:0x36
	v_mad_u32_u24 v0, v170, s62, v190
	s_nop 0
	v_lshl_add_u64 v[4:5], s[0:1], 0, v[0:1]
	v_lshlrev_b32_e32 v0, 3, v3
	v_and_b32_e32 v0, 0x78, v0
	v_lshlrev_b32_e32 v152, 1, v0
	v_mov_b32_e32 v153, v1
	v_lshl_add_u64 v[4:5], v[4:5], 0, v[152:153]
	s_add_i32 m0, s58, 0x10c00
	v_mad_u32_u24 v0, v170, s62, v191
	s_nop 0
	v_lshl_add_u64 v[4:5], s[0:1], 0, v[0:1]
	v_lshl_add_u64 v[4:5], v[4:5], 0, v[144:145]
	s_add_i32 m0, s58, 0x11000
	v_bitop3_b32 v3, v170, v2, 20 bitop3:0x36
	v_mad_u32_u24 v0, v170, s62, v192
	s_nop 0
	v_lshl_add_u64 v[4:5], s[0:1], 0, v[0:1]
	v_lshlrev_b32_e32 v0, 3, v3
	v_and_b32_e32 v0, 0x78, v0
	v_lshlrev_b32_e32 v150, 1, v0
	v_mov_b32_e32 v151, v1
	v_lshl_add_u64 v[4:5], v[4:5], 0, v[150:151]
	s_add_i32 m0, s58, 0x11400
	v_bitop3_b32 v3, v170, v2, 24 bitop3:0x36
	v_mad_u32_u24 v0, v170, s62, v193
	s_nop 0
	v_lshl_add_u64 v[4:5], s[0:1], 0, v[0:1]
	v_lshlrev_b32_e32 v0, 3, v3
	v_and_b32_e32 v0, 0x78, v0
	v_lshlrev_b32_e32 v154, 1, v0
	v_mov_b32_e32 v155, v1
	v_lshl_add_u64 v[4:5], v[4:5], 0, v[154:155]
	s_add_i32 m0, s58, 0x11800
	v_bitop3_b32 v3, v170, v2, 28 bitop3:0x36
	v_mad_u32_u24 v0, v170, s62, v194
	s_nop 0
	v_lshl_add_u64 v[4:5], s[0:1], 0, v[0:1]
	v_lshlrev_b32_e32 v0, 3, v3
	s_lshl_b32 s0, s56, 3
	v_and_b32_e32 v0, 0x78, v0
	v_or_b32_e32 v158, s0, v170
	v_lshlrev_b32_e32 v156, 1, v0
	s_lshl_b32 s92, s56, 11
	v_bitop3_b32 v0, s0, v2, v170 bitop3:0x36
	s_lshl_b32 s56, s56, 1
	v_ashrrev_i32_e32 v159, 31, v158
	v_mov_b32_e32 v157, v1
	v_and_b32_e32 v145, 15, v2
	v_lshlrev_b32_e32 v3, 2, v170
	s_and_b32 s0, s56, 2
	v_lshl_add_u64 v[6:7], v[158:159], 0, s[20:21]
	v_mov_b64_e32 v[8:9], s[54:55]
	v_lshlrev_b32_e32 v0, 3, v0
	v_lshl_add_u64 v[4:5], v[4:5], 0, v[156:157]
	s_add_i32 m0, s58, 0x11c00
	v_bitop3_b32 v74, s0, v145, v3 bitop3:0x36
	v_mad_u64_u32 v[10:11], s[0:1], v6, s62, v[8:9]
	v_and_b32_e32 v0, 0x78, v0
	s_nop 0
	v_mad_i32_i24 v11, v7, s62, v11
	v_lshlrev_b32_e32 v4, 1, v0
	v_mov_b32_e32 v5, v1
	v_lshl_add_u64 v[10:11], v[10:11], 0, v[4:5]
	s_add_i32 s57, s92, 0
	v_lshl_add_u64 v[10:11], v[10:11], 0, s[24:25]
	s_mov_b32 m0, s57
	s_or_b32 s56, s56, 1
	global_load_lds_dwordx4 v[10:11], off
	v_mov_b64_e32 v[10:11], s[52:53]
	v_mad_u64_u32 v[12:13], s[0:1], v6, s62, v[10:11]
	s_lshl_b32 s0, s56, 2
	v_mad_i32_i24 v13, v7, s62, v13
	v_lshlrev_b32_e32 v0, 4, v74
	v_or_b32_e32 v160, s0, v170
	v_lshl_add_u64 v[6:7], v[12:13], 0, v[0:1]
	v_bitop3_b32 v0, s0, v2, v170 bitop3:0x36
	v_ashrrev_i32_e32 v161, 31, v160
	s_and_b32 s0, s56, 3
	v_lshl_add_u64 v[12:13], v[160:161], 0, s[20:21]
	v_lshlrev_b32_e32 v0, 3, v0
	s_add_i32 m0, s57, 0x8000
	v_bitop3_b32 v5, s0, v145, v3 bitop3:0x36
	v_mad_u64_u32 v[8:9], s[0:1], v12, s62, v[8:9]
	v_and_b32_e32 v0, 0x78, v0
	global_load_lds_dwordx4 v[6:7], off
	v_mad_i32_i24 v9, v13, s62, v9
	v_lshlrev_b32_e32 v6, 1, v0
	v_mov_b32_e32 v7, v1
	s_lshl_b32 s93, s56, 10
	v_lshl_add_u64 v[8:9], v[8:9], 0, v[6:7]
	s_add_i32 s56, s93, 0
	v_lshl_add_u64 v[8:9], v[8:9], 0, s[24:25]
	s_mov_b32 m0, s56
	v_lshlrev_b32_e32 v0, 4, v5
	global_load_lds_dwordx4 v[8:9], off
	v_mad_u64_u32 v[8:9], s[0:1], v12, s62, v[10:11]
	v_mad_i32_i24 v9, v13, s62, v9
	v_lshl_add_u64 v[8:9], v[8:9], 0, v[0:1]
	s_add_i32 m0, s56, 0x8000
	s_lshl_b32 s75, s94, 7
	global_load_lds_dwordx4 v[8:9], off
	v_cmp_gt_i32_e32 vcc, s75, v2
	s_and_saveexec_b64 s[0:1], vcc
	s_cbranch_execz .LBB0_415
	s_lshl_b32 s76, s2, 3
	s_lshl_b32 s2, s3, 2
	s_add_u32 s2, s77, s2
	v_and_b32_e32 v0, 0x7f, v2
	s_addc_u32 s3, s78, 0
	v_lshlrev_b32_e32 v0, 2, v0
	v_add_u32_e32 v3, 0x200, v2
	v_lshl_add_u64 v[8:9], s[2:3], 0, v[0:1]
	v_max_i32_e32 v0, s75, v3
	v_xad_u32 v7, v2, -1, v0
	v_cmp_lt_u32_e32 vcc, s63, v7
	s_mov_b64 s[56:57], -1
	v_mov_b32_e32 v0, v2
	s_and_saveexec_b64 s[2:3], vcc
	s_cbranch_execz .LBB0_412
	v_lshrrev_b32_e32 v0, 9, v7
	v_add_u32_e32 v10, -1, v0
	v_lshrrev_b32_e32 v7, 1, v10
	v_add_u32_e32 v7, 1, v7
	v_cmp_lt_u32_e32 vcc, 5, v10
	v_mov_b32_e32 v14, 0
	v_mov_b64_e32 v[10:11], v[2:3]
	s_and_saveexec_b64 s[56:57], vcc
	s_cbranch_execz .LBB0_408
	v_and_b32_e32 v12, -4, v7
	v_lshl_add_u32 v13, v2, 2, s64
	s_mov_b32 s96, 0
	s_mov_b64 s[58:59], 0
	v_mov_b64_e32 v[10:11], v[2:3]

.LBB0_421:
	v_lshlrev_b32_e32 v0, 3, v74
	v_lshlrev_b32_e32 v3, 3, v5
	v_lshl_add_u64 v[164:165], v[0:1], 1, s[52:53]
	v_lshlrev_b32_e32 v0, 1, v3
	v_and_b32_e32 v174, 63, v2
	v_mov_b32_e32 v5, v1
	v_lshl_add_u64 v[168:169], s[52:53], 0, v[0:1]
	v_lshlrev_b32_e32 v180, 2, v72
	v_bfe_u32 v0, v2, 2, 2
	v_lshrrev_b32_e32 v3, 3, v2
	v_bfe_u32 v2, v2, 1, 1
	v_lshl_add_u64 v[162:163], s[54:55], 0, v[4:5]
	v_and_or_b32 v2, v3, 2, v2
	v_lshlrev_b32_e32 v3, 2, v0
	v_lshlrev_b32_e32 v5, 3, v174
	v_or_b32_e32 v0, v180, v0
	v_or_b32_e32 v4, v3, v72
	v_and_b32_e32 v181, 8, v5
	v_xor_b32_e32 v5, v72, v145
	v_lshlrev_b32_e32 v203, 8, v0
	v_bitop3_b32 v0, v3, v2, v72 bitop3:0x36
	v_lshlrev_b32_e32 v182, 4, v5
	v_bitop3_b32 v5, v72, v145, 2 bitop3:0x36
	v_lshlrev_b32_e32 v204, 4, v0
	v_bitop3_b32 v0, v4, v2, 2 bitop3:0x36
	v_lshlrev_b32_e32 v183, 4, v5
	v_bitop3_b32 v5, v72, v145, 4 bitop3:0x36
	v_lshlrev_b32_e32 v205, 4, v0
	v_or_b32_e32 v0, 4, v2
	v_lshlrev_b32_e32 v184, 4, v5
	v_bitop3_b32 v5, v72, v145, 6 bitop3:0x36
	v_bitop3_b32 v0, v4, v0, 2 bitop3:0x36
	v_lshlrev_b32_e32 v185, 4, v5
	v_bitop3_b32 v5, v72, v145, 8 bitop3:0x36
	v_lshlrev_b32_e32 v207, 4, v0
	v_or_b32_e32 v0, 8, v2
	v_lshlrev_b32_e32 v186, 4, v5
	v_bitop3_b32 v5, v72, v145, 10 bitop3:0x36
	v_bitop3_b32 v0, v4, v0, 2 bitop3:0x36
	v_lshlrev_b32_e32 v200, 4, v5
	v_bitop3_b32 v5, v72, v145, 12 bitop3:0x36
	v_bitop3_b32 v3, v2, v4, 4 bitop3:0x36
	v_lshlrev_b32_e32 v209, 4, v0
	v_or_b32_e32 v0, 12, v2
	v_mov_b32_e32 v7, v1
	v_lshlrev_b32_e32 v201, 4, v5
	v_bitop3_b32 v5, v72, v145, 14 bitop3:0x36
	v_lshlrev_b32_e32 v206, 4, v3
	v_bitop3_b32 v3, v2, v4, 8 bitop3:0x36
	v_bitop3_b32 v2, v2, v4, 12 bitop3:0x36
	v_bitop3_b32 v0, v4, v0, 2 bitop3:0x36
	v_mov_b32_e32 v14, v1
	v_mov_b32_e32 v15, v1
	v_lshlrev_b32_e32 v176, 3, v72
	s_lshl_b32 s56, s94, 2
	v_lshl_add_u64 v[166:167], s[54:55], 0, v[6:7]
	v_lshlrev_b32_e32 v178, 8, v73
	v_lshlrev_b32_e32 v202, 4, v5
	v_lshlrev_b32_e32 v208, 4, v3
	v_lshlrev_b32_e32 v210, 4, v2
	v_lshlrev_b32_e32 v211, 4, v0
	v_mov_b32_e32 v0, v1
	v_mov_b32_e32 v2, v1
	v_mov_b32_e32 v3, v1
	v_mov_b32_e32 v4, v1
	v_mov_b32_e32 v5, v1
	v_mov_b32_e32 v6, v1
	v_mov_b32_e32 v8, v1
	v_mov_b32_e32 v9, v1
	v_mov_b32_e32 v10, v1
	v_mov_b32_e32 v11, v1
	v_mov_b32_e32 v12, v1
	v_mov_b32_e32 v13, v1
	v_mov_b64_e32 v[30:31], v[14:15]
	v_mov_b64_e32 v[46:47], v[14:15]
	v_mov_b64_e32 v[62:63], v[14:15]
	v_mov_b64_e32 v[78:79], v[14:15]
	v_or_b32_e32 v147, 4, v170
	v_or_b32_e32 v149, 8, v170
	v_or_b32_e32 v153, 12, v170
	v_or_b32_e32 v151, 20, v170
	v_or_b32_e32 v155, 24, v170
	v_or_b32_e32 v157, 28, v170
	s_add_i32 s56, s56, 4
	s_or_b32 s54, s95, 31
	v_add_u32_e32 v179, 0, v178
	s_mov_b32 s55, 0
	v_mov_b32_e32 v212, 0
	v_mov_b32_e32 v213, 0xf149f2ca
	s_mov_b32 s57, 0
	v_mov_b64_e32 v[28:29], v[12:13]
	v_mov_b64_e32 v[26:27], v[10:11]
	v_mov_b64_e32 v[24:25], v[8:9]
	v_mov_b64_e32 v[22:23], v[6:7]
	v_mov_b64_e32 v[20:21], v[4:5]
	v_mov_b64_e32 v[18:19], v[2:3]
	v_mov_b64_e32 v[16:17], v[0:1]
	v_mov_b64_e32 v[44:45], v[12:13]
	v_mov_b64_e32 v[42:43], v[10:11]
	v_mov_b64_e32 v[40:41], v[8:9]
	v_mov_b64_e32 v[38:39], v[6:7]
	v_mov_b64_e32 v[36:37], v[4:5]
	v_mov_b64_e32 v[34:35], v[2:3]
	v_mov_b64_e32 v[32:33], v[0:1]
	v_mov_b64_e32 v[60:61], v[12:13]
	v_mov_b64_e32 v[58:59], v[10:11]
	v_mov_b64_e32 v[56:57], v[8:9]
	v_mov_b64_e32 v[54:55], v[6:7]
	v_mov_b64_e32 v[52:53], v[4:5]
	v_mov_b64_e32 v[50:51], v[2:3]
	v_mov_b64_e32 v[48:49], v[0:1]
	v_mov_b64_e32 v[76:77], v[12:13]
	v_mov_b64_e32 v[74:75], v[10:11]
	v_mov_b64_e32 v[72:73], v[8:9]
	v_mov_b64_e32 v[70:71], v[6:7]
	v_mov_b64_e32 v[68:69], v[4:5]
	v_mov_b64_e32 v[66:67], v[2:3]
	v_mov_b64_e32 v[64:65], v[0:1]
	s_mov_b32 s59, 0
	ds_read_b32 v246, v173
	s_waitcnt lgkmcnt(0)
	v_cmp_gt_u32_e32 vcc, 0x180, v246
	s_nop 1
	v_cndmask_b32_e64 v252, 0, 1, vcc
	v_cmp_gt_u32_e32 vcc, 0xc0, v246
	s_nop 1
	v_cndmask_b32_e64 v253, 0, 1, vcc
	v_mul_u32_u24_e32 v255, 0x5c0, v252
	v_mul_u32_u24_e32 v247, 0xc0, v253
	v_add_u32_e32 v255, v255, v247
	v_sub_u32_e32 v255, 0x680, v255
	v_sub_u32_e32 v255, v246, v255
	v_add_u32_e32 v252, v252, v253
	v_mad_u32_u24 v252, v252, 3, 1
	v_lshrrev_b32_e32 v253, 6, v255
	v_sub_u32_e32 v252, v252, v253
	v_bfe_u32 v247, v255, 3, 3
	v_lshlrev_b32_e32 v247, 11, v247
	v_lshl_add_u32 v247, v252, 8, v247
	v_and_b32_e32 v253, 7, v255
	v_lshlrev_b32_e32 v248, 8, v253
	v_mov_b32_e32 v249, 0x1800
	v_mov_b32_e32 v250, v247
	v_add_u32_e32 v251, 0x800, v248
	v_subrev_u32_e32 v255, 0x180, v246
	v_cmp_gt_u32_e32 vcc, 0x300, v255
	s_nop 3
	s_mov_b64 s[98:99], vcc
	v_bfe_u32 v246, v255, 5, 3
	v_lshlrev_b32_e32 v246, 11, v246
	v_and_b32_e32 v253, 7, v255
	v_lshl_add_u32 v252, v253, 8, v246
	v_cndmask_b32_e64 v247, v247, v252, s[98:99]
	v_lshlrev_b32_e32 v252, 8, v253
	v_and_b32_e32 v253, 0xfffffe00, v252
	v_cmp_le_u32_e32 vcc, 0x200, v255
	s_nop 1
	v_cndmask_b32_e32 v253, v253, v252, vcc
	v_cmp_le_u32_e32 vcc, 0x100, v255
	s_nop 1
	v_cndmask_b32_e64 v253, 0, v253, vcc
	v_subrev_u32_e32 v252, 0x80, v252
	v_max_i32_e32 v252, v252, v253
	v_add_u32_e32 v252, v252, v246
	v_cndmask_b32_e64 v250, v250, v252, s[98:99]
	v_lshrrev_b32_e32 v252, 8, v255
	v_bfe_u32 v253, v255, 3, 2
	v_lshl_add_u32 v252, v252, 2, v253
	v_lshlrev_b32_e32 v252, 8, v252
	v_add_u32_e32 v253, 0x2000, v252
	v_cndmask_b32_e64 v248, v248, v253, s[98:99]
	v_add_u32_e32 v253, 0x2c00, v252
	v_cndmask_b32_e64 v251, v251, v253, s[98:99]
	v_cndmask_b32_e64 v249, v249, 0, s[98:99]
	v_subrev_u32_e32 v255, 0x300, v255
	v_cmp_gt_u32_e32 vcc, 0x200, v255
	s_nop 3
	s_mov_b64 s[100:101], vcc
	v_lshrrev_b32_e32 v252, 6, v255
	v_lshlrev_b32_e32 v252, 11, v252
	v_bfe_u32 v253, v255, 1, 3
	v_lshl_add_u32 v252, v253, 8, v252
	v_cndmask_b32_e64 v247, v247, v252, s[100:101]
	v_cndmask_b32_e64 v250, v250, v252, s[100:101]
	v_bfe_u32 v252, v255, 4, 2
	v_lshlrev_b32_e32 v252, 9, v252
	v_add_u32_e32 v252, 0x4800, v252
	v_cndmask_b32_e64 v248, v248, v252, s[100:101]
	v_add_u32_e32 v253, 0x100, v252
	v_cndmask_b32_e64 v251, v251, v253, s[100:101]
	v_and_b32_e32 v252, 1, v255
	v_lshlrev_b32_e32 v252, 8, v252
	v_add_u32_e32 v252, 0x800, v252
	v_cndmask_b32_e64 v249, v249, v252, s[100:101]
	v_lshrrev_b32_e32 v252, 6, v175
	v_lshlrev_b32_e32 v252, 5, v252
	v_bfe_u32 v253, v175, 4, 2
	v_add3_u32 v247, v247, v252, v253
	v_mul_u32_u24_e32 v247, 0x5800, v247
	v_add3_u32 v247, v247, v248, v249
	v_and_b32_e32 v252, 15, v175
	v_add_u32_e32 v248, 0, v253
	v_xor_b32_e32 v248, v252, v248
	v_lshlrev_b32_e32 v248, 4, v248
	v_add_u32_e32 v249, 4, v253
	v_xor_b32_e32 v249, v252, v249
	v_lshlrev_b32_e32 v249, 4, v249
	v_add_u32_e32 v250, 8, v253
	v_xor_b32_e32 v250, v252, v250
	v_lshlrev_b32_e32 v250, 4, v250
	v_add_u32_e32 v251, 12, v253
	v_xor_b32_e32 v251, v252, v251
	v_lshlrev_b32_e32 v251, 4, v251
	v_readfirstlane_b32 s98, v175
	s_add_u32 s100, s38, 0xba00000
	s_addc_u32 s101, s39, 0
	s_lshr_b32 s98, s98, 6
	s_lshl_b32 s98, s98, 13
	s_add_i32 s98, s98, 0x10000
	v_add_u32_e32 v254, v247, v248
	v_mov_b32_e32 v255, 0
	v_lshl_add_u64 v[254:255], s[100:101], 0, v[254:255]
	s_add_i32 m0, s98, 0x0
	v_add_u32_e32 v247, 0x16000, v247
	global_load_lds_dwordx4 v[254:255], off
	v_add_u32_e32 v254, v247, v249
	v_mov_b32_e32 v255, 0
	v_lshl_add_u64 v[254:255], s[100:101], 0, v[254:255]
	s_add_i32 m0, s98, 0x400
	v_add_u32_e32 v247, 0x16000, v247
	global_load_lds_dwordx4 v[254:255], off
	v_add_u32_e32 v254, v247, v250
	v_mov_b32_e32 v255, 0
	v_lshl_add_u64 v[254:255], s[100:101], 0, v[254:255]
	s_add_i32 m0, s98, 0x800
	v_add_u32_e32 v247, 0x16000, v247
	global_load_lds_dwordx4 v[254:255], off
	v_add_u32_e32 v254, v247, v251
	v_mov_b32_e32 v255, 0
	v_lshl_add_u64 v[254:255], s[100:101], 0, v[254:255]
	s_add_i32 m0, s98, 0xc00
	v_add_u32_e32 v247, 0x16000, v247
	global_load_lds_dwordx4 v[254:255], off
	v_add_u32_e32 v254, v247, v248
	v_mov_b32_e32 v255, 0
	v_lshl_add_u64 v[254:255], s[100:101], 0, v[254:255]
	s_add_i32 m0, s98, 0x1000
	v_add_u32_e32 v247, 0x16000, v247
	global_load_lds_dwordx4 v[254:255], off
	v_add_u32_e32 v254, v247, v249
	v_mov_b32_e32 v255, 0
	v_lshl_add_u64 v[254:255], s[100:101], 0, v[254:255]
	s_add_i32 m0, s98, 0x1400
	v_add_u32_e32 v247, 0x16000, v247
	global_load_lds_dwordx4 v[254:255], off
	v_add_u32_e32 v254, v247, v250
	v_mov_b32_e32 v255, 0
	v_lshl_add_u64 v[254:255], s[100:101], 0, v[254:255]
	s_add_i32 m0, s98, 0x1800
	v_add_u32_e32 v247, 0x16000, v247
	global_load_lds_dwordx4 v[254:255], off
	v_add_u32_e32 v254, v247, v251
	v_mov_b32_e32 v255, 0
	v_lshl_add_u64 v[254:255], s[100:101], 0, v[254:255]
	s_add_i32 m0, s98, 0x1c00
	s_nop 0
	global_load_lds_dwordx4 v[254:255], off
	s_branch .Lzd_entry_1

.Lzd_entry_1:
	s_add_i32 s58, s59, 1
	s_cmp_ge_u32 s58, s56
	s_barrier
	s_cbranch_scc1 .LBB0_426
	s_cmp_lt_u32 s59, 3
	s_cselect_b32 s0, s20, 0xffffff00
	s_add_i32 s0, s0, s57
	s_add_i32 s0, s0, 64
	s_ashr_i32 s1, s0, 31
	s_add_i32 s2, s55, 0x4000
	s_and_b32 s52, s2, 0x4000
	v_lshl_add_u64 v[2:3], s[0:1], 0, v[158:159]
	v_mad_u64_u32 v[4:5], s[2:3], v2, s62, v[162:163]
	s_add_i32 s52, s52, 0
	v_mad_i32_i24 v5, v3, s62, v5
	s_add_i32 s53, s52, s92
	v_lshl_add_u64 v[4:5], v[4:5], 0, s[24:25]
	s_mov_b32 m0, s53
	s_nop 0
	global_load_lds_dwordx4 v[4:5], off
	v_mad_u64_u32 v[4:5], s[2:3], v2, s62, v[164:165]
	v_mad_i32_i24 v5, v3, s62, v5
	s_add_i32 m0, s53, 0x8000
	v_lshl_add_u64 v[2:3], s[0:1], 0, v[160:161]
	global_load_lds_dwordx4 v[4:5], off
	v_mad_u64_u32 v[4:5], s[0:1], v2, s62, v[166:167]
	v_mad_i32_i24 v5, v3, s62, v5
	s_add_i32 s2, s52, s93
	v_lshl_add_u64 v[4:5], v[4:5], 0, s[24:25]
	s_mov_b32 m0, s2
	s_nop 0
	global_load_lds_dwordx4 v[4:5], off
	v_mad_u64_u32 v[4:5], s[0:1], v2, s62, v[168:169]
	v_mad_i32_i24 v5, v3, s62, v5
	s_add_i32 m0, s2, 0x8000
	s_nop 0
	global_load_lds_dwordx4 v[4:5], off

.LBB0_438:
	s_andn2_b64 vcc, exec, s[52:53]
	s_cbranch_vccnz .LBB0_263
	s_ashr_i32 s0, s89, 6
	v_mov_b32_e32 v2, v175
	s_bfe_u32 s2, s89, 0x30003
	s_sub_i32 s93, 7, s0
	s_lshl_b32 s20, s93, 8
	v_readfirstlane_b32 s0, v2
	s_ashr_i32 s56, s0, 6
	s_lshl_b32 s0, s2, 11
	s_add_i32 s57, s20, s0
	s_mul_i32 s1, s57, 0x5800
	s_mul_hi_u32 s0, s57, 0x5800
	s_add_u32 s1, s6, s1
	s_addc_u32 s52, s7, s0
	s_lshl_b32 s0, s89, 7
	s_and_b32 s3, s0, 0x380
	s_lshl_b32 s60, s3, 1
	s_add_u32 s0, s1, s60
	s_addc_u32 s1, s52, 0
	s_mul_i32 s52, s2, 0x2c00000
	s_add_u32 s52, s6, s52
	s_addc_u32 s53, s7, 0
	s_lshl_b32 s94, s56, 5
	v_and_b32_e32 v73, 31, v2
	s_add_u32 s54, s52, s60
	v_or_b32_e32 v172, s94, v73
	v_mov_b64_e32 v[4:5], s[0:1]
	s_addc_u32 s55, s53, 0
	v_mad_i64_i32 v[4:5], s[0:1], v172, s62, v[4:5]
	s_add_u32 s52, s54, 0x1000
	s_addc_u32 s53, s55, 0
	s_lshl_b32 s0, s56, 13
	s_add_i32 s58, s0, 0
	s_add_i32 s61, s58, 0x10000
	s_ashr_i32 s0, s94, 31
	s_add_u32 s89, s57, s94
	s_addc_u32 s90, 0, s0
	s_mul_i32 s0, s90, 0x5800
	s_mul_hi_u32 s1, s89, 0x5800
	s_add_i32 s1, s1, s0
	s_mul_i32 s0, s89, 0x5800
	s_add_u32 s0, s6, s0
	s_addc_u32 s1, s7, s1
	s_add_u32 s0, s0, s60
	v_bfe_u32 v72, v2, 5, 1
	s_addc_u32 s1, s1, 0
	v_lshlrev_b32_e32 v0, 4, v72
	s_add_u32 s0, s0, 0x1800
	v_bfe_u32 v170, v2, 4, 2
	v_lshl_add_u64 v[4:5], v[4:5], 0, v[0:1]
	s_addc_u32 s1, s1, 0
	v_xor_b32_e32 v3, v170, v2
	v_mul_u32_u24_e32 v0, 0x5800, v170
	global_load_dwordx4 v[112:115], v[4:5], off
	global_load_dwordx4 v[116:119], v[4:5], off offset:32
	global_load_dwordx4 v[120:123], v[4:5], off offset:64
	global_load_dwordx4 v[124:127], v[4:5], off offset:96
	global_load_dwordx4 v[128:131], v[4:5], off offset:128
	global_load_dwordx4 v[132:135], v[4:5], off offset:160
	global_load_dwordx4 v[136:139], v[4:5], off offset:192
	global_load_dwordx4 v[140:143], v[4:5], off offset:224
	v_lshl_add_u64 v[4:5], s[0:1], 0, v[0:1]
	v_lshlrev_b32_e32 v0, 3, v3
	v_and_b32_e32 v0, 0x78, v0
	v_lshlrev_b32_e32 v144, 1, v0
	v_mov_b32_e32 v145, v1
	v_lshl_add_u64 v[4:5], v[4:5], 0, v[144:145]
	s_mov_b32 m0, s61
	v_bitop3_b32 v3, v170, v2, 4 bitop3:0x36
	v_mad_u32_u24 v0, v170, s62, v188
	s_nop 0
	v_lshl_add_u64 v[4:5], s[0:1], 0, v[0:1]
	v_lshlrev_b32_e32 v0, 3, v3
	v_and_b32_e32 v0, 0x78, v0
	v_lshlrev_b32_e32 v146, 1, v0
	v_mov_b32_e32 v147, v1
	v_lshl_add_u64 v[4:5], v[4:5], 0, v[146:147]
	s_add_i32 m0, s58, 0x10400
	v_bitop3_b32 v3, v170, v2, 8 bitop3:0x36
	v_mad_u32_u24 v0, v170, s62, v189
	s_nop 0
	v_lshl_add_u64 v[4:5], s[0:1], 0, v[0:1]
	v_lshlrev_b32_e32 v0, 3, v3
	v_and_b32_e32 v0, 0x78, v0
	v_lshlrev_b32_e32 v148, 1, v0
	v_mov_b32_e32 v149, v1
	v_lshl_add_u64 v[4:5], v[4:5], 0, v[148:149]
	s_add_i32 m0, s58, 0x10800
	v_bitop3_b32 v3, v170, v2, 12 bitop3:0x36
	v_mad_u32_u24 v0, v170, s62, v190
	s_nop 0
	v_lshl_add_u64 v[4:5], s[0:1], 0, v[0:1]
	v_lshlrev_b32_e32 v0, 3, v3
	v_and_b32_e32 v0, 0x78, v0
	v_lshlrev_b32_e32 v152, 1, v0
	v_mov_b32_e32 v153, v1
	v_lshl_add_u64 v[4:5], v[4:5], 0, v[152:153]
	s_add_i32 m0, s58, 0x10c00
	v_mad_u32_u24 v0, v170, s62, v191
	s_nop 0
	v_lshl_add_u64 v[4:5], s[0:1], 0, v[0:1]
	v_lshl_add_u64 v[4:5], v[4:5], 0, v[144:145]
	s_add_i32 m0, s58, 0x11000
	v_bitop3_b32 v3, v170, v2, 20 bitop3:0x36
	v_mad_u32_u24 v0, v170, s62, v192
	s_nop 0
	v_lshl_add_u64 v[4:5], s[0:1], 0, v[0:1]
	v_lshlrev_b32_e32 v0, 3, v3
	v_and_b32_e32 v0, 0x78, v0
	v_lshlrev_b32_e32 v150, 1, v0
	v_mov_b32_e32 v151, v1
	v_lshl_add_u64 v[4:5], v[4:5], 0, v[150:151]
	s_add_i32 m0, s58, 0x11400
	v_bitop3_b32 v3, v170, v2, 24 bitop3:0x36
	v_mad_u32_u24 v0, v170, s62, v193
	s_nop 0
	v_lshl_add_u64 v[4:5], s[0:1], 0, v[0:1]
	v_lshlrev_b32_e32 v0, 3, v3
	v_and_b32_e32 v0, 0x78, v0
	v_lshlrev_b32_e32 v154, 1, v0
	v_mov_b32_e32 v155, v1
	v_lshl_add_u64 v[4:5], v[4:5], 0, v[154:155]
	s_add_i32 m0, s58, 0x11800
	v_bitop3_b32 v3, v170, v2, 28 bitop3:0x36
	v_mad_u32_u24 v0, v170, s62, v194
	s_nop 0
	v_lshl_add_u64 v[4:5], s[0:1], 0, v[0:1]
	v_lshlrev_b32_e32 v0, 3, v3
	s_lshl_b32 s0, s56, 3
	v_and_b32_e32 v0, 0x78, v0
	v_or_b32_e32 v158, s0, v170
	v_lshlrev_b32_e32 v156, 1, v0
	s_lshl_b32 s91, s56, 11
	v_bitop3_b32 v0, s0, v2, v170 bitop3:0x36
	s_lshl_b32 s56, s56, 1
	v_ashrrev_i32_e32 v159, 31, v158
	v_mov_b32_e32 v157, v1
	v_and_b32_e32 v145, 15, v2
	v_lshlrev_b32_e32 v3, 2, v170
	s_and_b32 s0, s56, 2
	v_lshl_add_u64 v[6:7], v[158:159], 0, s[20:21]
	v_mov_b64_e32 v[8:9], s[54:55]
	v_lshlrev_b32_e32 v0, 3, v0
	v_lshl_add_u64 v[4:5], v[4:5], 0, v[156:157]
	s_add_i32 m0, s58, 0x11c00
	v_bitop3_b32 v12, s0, v145, v3 bitop3:0x36
	v_mad_u64_u32 v[10:11], s[0:1], v6, s62, v[8:9]
	v_and_b32_e32 v0, 0x78, v0
	s_nop 0
	v_mad_i32_i24 v11, v7, s62, v11
	v_lshlrev_b32_e32 v4, 1, v0
	v_mov_b32_e32 v5, v1
	v_lshl_add_u64 v[10:11], v[10:11], 0, v[4:5]
	s_add_i32 s57, s91, 0
	v_lshl_add_u64 v[10:11], v[10:11], 0, s[24:25]
	s_mov_b32 m0, s57
	s_or_b32 s56, s56, 1
	global_load_lds_dwordx4 v[10:11], off
	v_mov_b64_e32 v[10:11], s[52:53]
	v_mad_u64_u32 v[14:15], s[0:1], v6, s62, v[10:11]
	s_lshl_b32 s0, s56, 2
	v_mad_i32_i24 v15, v7, s62, v15
	v_lshlrev_b32_e32 v0, 4, v12
	v_or_b32_e32 v160, s0, v170
	v_lshl_add_u64 v[6:7], v[14:15], 0, v[0:1]
	v_bitop3_b32 v0, s0, v2, v170 bitop3:0x36
	v_ashrrev_i32_e32 v161, 31, v160
	s_and_b32 s0, s56, 3
	v_lshl_add_u64 v[14:15], v[160:161], 0, s[20:21]
	v_lshlrev_b32_e32 v0, 3, v0
	s_add_i32 m0, s57, 0x8000
	v_bitop3_b32 v5, s0, v145, v3 bitop3:0x36
	v_mad_u64_u32 v[8:9], s[0:1], v14, s62, v[8:9]
	v_and_b32_e32 v0, 0x78, v0
	global_load_lds_dwordx4 v[6:7], off
	v_mad_i32_i24 v9, v15, s62, v9
	v_lshlrev_b32_e32 v6, 1, v0
	v_mov_b32_e32 v7, v1
	s_lshl_b32 s92, s56, 10
	v_lshl_add_u64 v[8:9], v[8:9], 0, v[6:7]
	s_add_i32 s56, s92, 0
	v_lshl_add_u64 v[8:9], v[8:9], 0, s[24:25]
	s_mov_b32 m0, s56
	v_lshlrev_b32_e32 v0, 4, v5
	global_load_lds_dwordx4 v[8:9], off
	v_mad_u64_u32 v[8:9], s[0:1], v14, s62, v[10:11]
	v_mad_i32_i24 v9, v15, s62, v9
	v_lshl_add_u64 v[8:9], v[8:9], 0, v[0:1]
	s_add_i32 m0, s56, 0x8000
	s_lshl_b32 s66, s93, 7
	global_load_lds_dwordx4 v[8:9], off
	v_cmp_gt_i32_e32 vcc, s66, v2
	s_and_saveexec_b64 s[0:1], vcc
	s_cbranch_execz .LBB0_452
	s_lshl_b32 s75, s2, 3
	s_lshl_b32 s2, s3, 2
	s_add_u32 s2, s77, s2
	v_and_b32_e32 v0, 0x7f, v2
	s_addc_u32 s3, s78, 0
	v_lshlrev_b32_e32 v0, 2, v0
	v_add_u32_e32 v3, 0x200, v2
	v_lshl_add_u64 v[8:9], s[2:3], 0, v[0:1]
	v_max_i32_e32 v0, s66, v3
	v_xad_u32 v7, v2, -1, v0
	v_cmp_lt_u32_e32 vcc, s63, v7
	s_mov_b64 s[56:57], -1
	v_mov_b32_e32 v0, v2
	s_and_saveexec_b64 s[2:3], vcc
	s_cbranch_execz .LBB0_449
	v_lshrrev_b32_e32 v0, 9, v7
	v_add_u32_e32 v10, -1, v0
	v_lshrrev_b32_e32 v7, 1, v10
	v_add_u32_e32 v7, 1, v7
	v_cmp_lt_u32_e32 vcc, 5, v10
	v_mov_b32_e32 v15, 0
	v_mov_b64_e32 v[10:11], v[2:3]
	s_and_saveexec_b64 s[56:57], vcc
	s_cbranch_execz .LBB0_445
	v_and_b32_e32 v13, -4, v7
	v_lshl_add_u32 v14, v2, 2, s64
	s_mov_b32 s76, 0
	s_mov_b64 s[58:59], 0
	v_mov_b64_e32 v[10:11], v[2:3]

.LBB0_453:
	v_mov_b32_e32 v177, v78
	ds_read_b128 v[78:81], v5
	ds_read_b128 v[82:85], v5 offset:16
	ds_read_b128 v[86:89], v5 offset:64
	ds_read_b128 v[90:93], v5 offset:80
	ds_read_b128 v[94:97], v5 offset:128
	ds_read_b128 v[98:101], v5 offset:144
	ds_read_b128 v[102:105], v5 offset:192
	ds_read_b128 v[106:109], v5 offset:208
	ds_read_b128 v[162:165], v5 offset:256
	ds_read_b128 v[166:169], v5 offset:272
	ds_read_b128 v[178:181], v5 offset:320
	ds_read_b128 v[182:185], v5 offset:336
	ds_read_b128 v[200:203], v5 offset:384
	ds_read_b128 v[204:207], v5 offset:400
	ds_read_b128 v[208:211], v5 offset:448
	ds_read_b128 v[212:215], v5 offset:464
	s_waitcnt lgkmcnt(13)
	v_mov_b32_e32 v111, v86
	v_mov_b32_e32 v86, v79
	v_mov_b32_e32 v110, v78
	v_pk_mul_f32 v[86:87], v[86:87], v[10:11]
	v_mov_b32_e32 v78, v80
	v_mov_b32_e32 v79, v88
	v_mov_b32_e32 v88, v81
	s_waitcnt lgkmcnt(12)
	v_mov_b32_e32 v81, v90
	v_mov_b32_e32 v90, v83
	v_mov_b32_e32 v83, v92
	v_mov_b32_e32 v92, v85
	s_waitcnt lgkmcnt(9)
	v_mov_b32_e32 v85, v102
	v_mov_b32_e32 v102, v95
	v_pk_fma_f32 v[86:87], v[110:111], v[8:9], v[86:87]
	v_mov_b32_e32 v80, v82
	v_mov_b32_e32 v82, v84
	v_mov_b32_e32 v84, v94
	v_pk_mul_f32 v[102:103], v[102:103], v[26:27]
	v_pk_fma_f32 v[78:79], v[78:79], v[12:13], v[86:87]
	v_mov_b32_e32 v94, v96
	v_mov_b32_e32 v95, v104
	v_mov_b32_e32 v104, v97
	s_waitcnt lgkmcnt(8)
	v_mov_b32_e32 v97, v106
	v_mov_b32_e32 v106, v99
	v_mov_b32_e32 v99, v108
	v_mov_b32_e32 v108, v101
	s_waitcnt lgkmcnt(5)
	v_mov_b32_e32 v101, v178
	v_mov_b32_e32 v178, v163
	v_pk_fma_f32 v[84:85], v[84:85], v[24:25], v[102:103]
	v_pk_fma_f32 v[78:79], v[88:89], v[14:15], v[78:79]
	v_mov_b32_e32 v96, v98
	v_mov_b32_e32 v98, v100
	v_mov_b32_e32 v100, v162
	v_pk_mul_f32 v[178:179], v[178:179], v[42:43]
	v_pk_fma_f32 v[84:85], v[94:95], v[28:29], v[84:85]
	v_pk_fma_f32 v[78:79], v[80:81], v[16:17], v[78:79]
	v_mov_b32_e32 v162, v164
	v_mov_b32_e32 v163, v180
	v_mov_b32_e32 v180, v165
	s_waitcnt lgkmcnt(4)
	v_mov_b32_e32 v165, v182
	v_mov_b32_e32 v182, v167
	v_mov_b32_e32 v167, v184
	v_mov_b32_e32 v184, v169
	s_waitcnt lgkmcnt(1)
	v_mov_b32_e32 v169, v208
	v_mov_b32_e32 v208, v201
	v_pk_fma_f32 v[100:101], v[100:101], v[40:41], v[178:179]
	v_pk_fma_f32 v[84:85], v[104:105], v[30:31], v[84:85]
	v_pk_fma_f32 v[78:79], v[90:91], v[18:19], v[78:79]
	v_mov_b32_e32 v164, v166
	v_mov_b32_e32 v166, v168
	v_mov_b32_e32 v168, v200
	v_mov_b32_e32 v200, v202
	v_mov_b32_e32 v201, v210
	v_mov_b32_e32 v210, v203
	v_mov_b32_e32 v202, v204
	s_waitcnt lgkmcnt(0)
	v_mov_b32_e32 v203, v212
	v_mov_b32_e32 v212, v205
	v_mov_b32_e32 v204, v206
	v_mov_b32_e32 v205, v214
	v_mov_b32_e32 v214, v207
	v_pk_mul_f32 v[206:207], v[208:209], v[58:59]
	v_pk_fma_f32 v[86:87], v[162:163], v[44:45], v[100:101]
	v_pk_fma_f32 v[80:81], v[96:97], v[32:33], v[84:85]
	v_pk_fma_f32 v[78:79], v[82:83], v[20:21], v[78:79]
	v_pk_fma_f32 v[102:103], v[168:169], v[56:57], v[206:207]
	v_pk_fma_f32 v[86:87], v[180:181], v[46:47], v[86:87]
	v_pk_fma_f32 v[80:81], v[106:107], v[34:35], v[80:81]
	v_pk_fma_f32 v[78:79], v[92:93], v[22:23], v[78:79]
	v_pk_fma_f32 v[94:95], v[200:201], v[60:61], v[102:103]
	v_pk_fma_f32 v[84:85], v[164:165], v[48:49], v[86:87]
	v_pk_fma_f32 v[80:81], v[98:99], v[36:37], v[80:81]
	v_add_f32_e32 v78, 0, v78
	v_pk_fma_f32 v[88:89], v[210:211], v[62:63], v[94:95]
	v_pk_fma_f32 v[84:85], v[182:183], v[50:51], v[84:85]
	v_pk_fma_f32 v[80:81], v[108:109], v[38:39], v[80:81]
	v_add_f32_e32 v78, v78, v79
	v_pk_fma_f32 v[86:87], v[202:203], v[64:65], v[88:89]
	v_pk_fma_f32 v[82:83], v[166:167], v[52:53], v[84:85]
	v_add_f32_e32 v78, v78, v80
	v_pk_fma_f32 v[86:87], v[212:213], v[66:67], v[86:87]
	v_pk_fma_f32 v[82:83], v[184:185], v[54:55], v[82:83]
	v_add_f32_e32 v78, v78, v81
	v_pk_fma_f32 v[84:85], v[204:205], v[68:69], v[86:87]
	v_add_f32_e32 v78, v78, v82
	v_pk_fma_f32 v[84:85], v[214:215], v[70:71], v[84:85]
	v_add_f32_e32 v78, v78, v83
	v_add_f32_e32 v78, v78, v84
	v_add_f32_e32 v78, v78, v85
	v_mov_b32_e32 v79, v78
	s_nop 1
	v_permlane32_swap_b32_e32 v78, v79
	v_add_f32_e32 v79, v78, v79
	v_cmp_gt_f32_e32 vcc, v79, v76
	v_mov_b32_e32 v186, s56
	v_cmp_gt_f32_e64 s[0:1], v79, v77
	v_cndmask_b32_e32 v76, v76, v79, vcc
	s_add_i32 s56, s56, 1
	v_cndmask_b32_e64 v76, v76, v77, s[0:1]
	v_cndmask_b32_e64 v77, v77, v79, s[0:1]
	v_cmp_gt_f32_e64 s[2:3], v79, v7
	v_cndmask_b32_e32 v74, v74, v186, vcc
	v_cndmask_b32_e64 v80, v75, v186, s[0:1]
	v_add_u32_e32 v5, 0x200, v5
	s_cmp_lg_u32 s93, s56
	v_cndmask_b32_e64 v74, v74, v75, s[0:1]
	v_cndmask_b32_e64 v77, v77, v7, s[2:3]
	v_cndmask_b32_e64 v78, v177, v186, s[2:3]
	v_cndmask_b32_e64 v7, v7, v79, s[2:3]
	v_cndmask_b32_e64 v75, v80, v177, s[2:3]
	s_cbranch_scc1 .LBB0_453
	v_lshlrev_b32_e64 v5, v78, 1
	v_lshlrev_b32_e64 v7, v75, 1
	v_lshlrev_b32_e64 v8, v74, 1
	v_lshl_add_u64 v[164:165], v[0:1], 1, s[52:53]
	v_lshlrev_b32_e32 v0, 1, v3
	v_or3_b32 v178, v8, v5, v7
	v_mov_b32_e32 v5, v1
	v_lshl_add_u64 v[168:169], s[52:53], 0, v[0:1]
	v_lshlrev_b32_e32 v180, 2, v72
	v_bfe_u32 v0, v2, 2, 2
	v_lshrrev_b32_e32 v3, 3, v2
	v_bfe_u32 v2, v2, 1, 1
	v_lshl_add_u64 v[162:163], s[54:55], 0, v[4:5]
	v_and_or_b32 v2, v3, 2, v2
	v_lshlrev_b32_e32 v3, 2, v0
	v_lshlrev_b32_e32 v5, 3, v174
	v_or_b32_e32 v0, v180, v0
	v_or_b32_e32 v4, v3, v72
	v_and_b32_e32 v181, 8, v5
	v_xor_b32_e32 v5, v72, v145
	v_lshlrev_b32_e32 v203, 8, v0
	v_bitop3_b32 v0, v3, v2, v72 bitop3:0x36
	v_lshlrev_b32_e32 v182, 4, v5
	v_bitop3_b32 v5, v72, v145, 2 bitop3:0x36
	v_lshlrev_b32_e32 v204, 4, v0
	v_bitop3_b32 v0, v4, v2, 2 bitop3:0x36
	v_lshlrev_b32_e32 v183, 4, v5
	v_bitop3_b32 v5, v72, v145, 4 bitop3:0x36
	v_lshlrev_b32_e32 v205, 4, v0
	v_or_b32_e32 v0, 4, v2
	v_lshlrev_b32_e32 v184, 4, v5
	v_bitop3_b32 v5, v72, v145, 6 bitop3:0x36
	v_bitop3_b32 v0, v4, v0, 2 bitop3:0x36
	v_lshlrev_b32_e32 v185, 4, v5
	v_bitop3_b32 v5, v72, v145, 8 bitop3:0x36
	v_lshlrev_b32_e32 v207, 4, v0
	v_or_b32_e32 v0, 8, v2
	v_lshlrev_b32_e32 v186, 4, v5
	v_bitop3_b32 v5, v72, v145, 10 bitop3:0x36
	v_bitop3_b32 v0, v4, v0, 2 bitop3:0x36
	v_lshlrev_b32_e32 v200, 4, v5
	v_bitop3_b32 v5, v72, v145, 12 bitop3:0x36
	v_bitop3_b32 v3, v2, v4, 4 bitop3:0x36
	v_lshlrev_b32_e32 v209, 4, v0
	v_or_b32_e32 v0, 12, v2
	v_mov_b32_e32 v7, v1
	v_lshlrev_b32_e32 v201, 4, v5
	v_bitop3_b32 v5, v72, v145, 14 bitop3:0x36
	v_lshlrev_b32_e32 v206, 4, v3
	v_bitop3_b32 v3, v2, v4, 8 bitop3:0x36
	v_bitop3_b32 v2, v2, v4, 12 bitop3:0x36
	v_bitop3_b32 v0, v4, v0, 2 bitop3:0x36
	v_mov_b32_e32 v14, v1
	v_mov_b32_e32 v15, v1
	s_lshl_b32 s56, s93, 2
	v_lshl_add_u64 v[166:167], s[54:55], 0, v[6:7]
	v_lshlrev_b32_e32 v177, 8, v73
	v_lshlrev_b32_e32 v202, 4, v5
	v_lshlrev_b32_e32 v208, 4, v3
	v_lshlrev_b32_e32 v210, 4, v2
	v_lshlrev_b32_e32 v211, 4, v0
	v_mov_b32_e32 v0, v1
	v_mov_b32_e32 v2, v1
	v_mov_b32_e32 v3, v1
	v_mov_b32_e32 v4, v1
	v_mov_b32_e32 v5, v1
	v_mov_b32_e32 v6, v1
	v_mov_b32_e32 v8, v1
	v_mov_b32_e32 v9, v1
	v_mov_b32_e32 v10, v1
	v_mov_b32_e32 v11, v1
	v_mov_b32_e32 v12, v1
	v_mov_b32_e32 v13, v1
	v_mov_b64_e32 v[30:31], v[14:15]
	v_mov_b64_e32 v[46:47], v[14:15]
	v_mov_b64_e32 v[62:63], v[14:15]
	v_mov_b64_e32 v[78:79], v[14:15]
	s_add_i32 s56, s56, 4
	s_or_b32 s54, s94, 31
	v_add_u32_e32 v179, 0, v177
	s_mov_b32 s55, 0
	v_mov_b32_e32 v212, 0
	v_mov_b32_e32 v213, 0xf149f2ca
	s_mov_b32 s57, 0
	v_mov_b64_e32 v[28:29], v[12:13]
	v_mov_b64_e32 v[26:27], v[10:11]
	v_mov_b64_e32 v[24:25], v[8:9]
	v_mov_b64_e32 v[22:23], v[6:7]
	v_mov_b64_e32 v[20:21], v[4:5]
	v_mov_b64_e32 v[18:19], v[2:3]
	v_mov_b64_e32 v[16:17], v[0:1]
	v_mov_b64_e32 v[44:45], v[12:13]
	v_mov_b64_e32 v[42:43], v[10:11]
	v_mov_b64_e32 v[40:41], v[8:9]
	v_mov_b64_e32 v[38:39], v[6:7]
	v_mov_b64_e32 v[36:37], v[4:5]
	v_mov_b64_e32 v[34:35], v[2:3]
	v_mov_b64_e32 v[32:33], v[0:1]
	v_mov_b64_e32 v[60:61], v[12:13]
	v_mov_b64_e32 v[58:59], v[10:11]
	v_mov_b64_e32 v[56:57], v[8:9]
	v_mov_b64_e32 v[54:55], v[6:7]
	v_mov_b64_e32 v[52:53], v[4:5]
	v_mov_b64_e32 v[50:51], v[2:3]
	v_mov_b64_e32 v[48:49], v[0:1]
	v_mov_b64_e32 v[76:77], v[12:13]
	v_mov_b64_e32 v[74:75], v[10:11]
	v_mov_b64_e32 v[72:73], v[8:9]
	v_mov_b64_e32 v[70:71], v[6:7]
	v_mov_b64_e32 v[68:69], v[4:5]
	v_mov_b64_e32 v[66:67], v[2:3]
	v_mov_b64_e32 v[64:65], v[0:1]
	s_mov_b32 s59, 0
	ds_read_b32 v246, v173
	s_waitcnt lgkmcnt(0)
	v_cmp_gt_u32_e32 vcc, 0x180, v246
	s_nop 1
	v_cndmask_b32_e64 v252, 0, 1, vcc
	v_cmp_gt_u32_e32 vcc, 0xc0, v246
	s_nop 1
	v_cndmask_b32_e64 v253, 0, 1, vcc
	v_mul_u32_u24_e32 v255, 0x5c0, v252
	v_mul_u32_u24_e32 v247, 0xc0, v253
	v_add_u32_e32 v255, v255, v247
	v_sub_u32_e32 v255, 0x680, v255
	v_sub_u32_e32 v255, v246, v255
	v_add_u32_e32 v252, v252, v253
	v_mad_u32_u24 v252, v252, 3, 1
	v_lshrrev_b32_e32 v253, 6, v255
	v_sub_u32_e32 v252, v252, v253
	v_bfe_u32 v247, v255, 3, 3
	v_lshlrev_b32_e32 v247, 11, v247
	v_lshl_add_u32 v247, v252, 8, v247
	v_and_b32_e32 v253, 7, v255
	v_lshlrev_b32_e32 v248, 8, v253
	v_mov_b32_e32 v249, 0x1800
	v_mov_b32_e32 v250, v247
	v_add_u32_e32 v251, 0x800, v248
	v_subrev_u32_e32 v255, 0x180, v246
	v_cmp_gt_u32_e32 vcc, 0x300, v255
	s_nop 3
	s_mov_b64 s[98:99], vcc
	v_bfe_u32 v246, v255, 5, 3
	v_lshlrev_b32_e32 v246, 11, v246
	v_and_b32_e32 v253, 7, v255
	v_lshl_add_u32 v252, v253, 8, v246
	v_cndmask_b32_e64 v247, v247, v252, s[98:99]
	v_lshlrev_b32_e32 v252, 8, v253
	v_and_b32_e32 v253, 0xfffffe00, v252
	v_cmp_le_u32_e32 vcc, 0x200, v255
	s_nop 1
	v_cndmask_b32_e32 v253, v253, v252, vcc
	v_cmp_le_u32_e32 vcc, 0x100, v255
	s_nop 1
	v_cndmask_b32_e64 v253, 0, v253, vcc
	v_subrev_u32_e32 v252, 0x80, v252
	v_max_i32_e32 v252, v252, v253
	v_add_u32_e32 v252, v252, v246
	v_cndmask_b32_e64 v250, v250, v252, s[98:99]
	v_lshrrev_b32_e32 v252, 8, v255
	v_bfe_u32 v253, v255, 3, 2
	v_lshl_add_u32 v252, v252, 2, v253
	v_lshlrev_b32_e32 v252, 8, v252
	v_add_u32_e32 v253, 0x2000, v252
	v_cndmask_b32_e64 v248, v248, v253, s[98:99]
	v_add_u32_e32 v253, 0x2c00, v252
	v_cndmask_b32_e64 v251, v251, v253, s[98:99]
	v_cndmask_b32_e64 v249, v249, 0, s[98:99]
	v_subrev_u32_e32 v255, 0x300, v255
	v_cmp_gt_u32_e32 vcc, 0x200, v255
	s_nop 3
	s_mov_b64 s[100:101], vcc
	v_lshrrev_b32_e32 v252, 6, v255
	v_lshlrev_b32_e32 v252, 11, v252
	v_bfe_u32 v253, v255, 1, 3
	v_lshl_add_u32 v252, v253, 8, v252
	v_cndmask_b32_e64 v247, v247, v252, s[100:101]
	v_cndmask_b32_e64 v250, v250, v252, s[100:101]
	v_bfe_u32 v252, v255, 4, 2
	v_lshlrev_b32_e32 v252, 9, v252
	v_add_u32_e32 v252, 0x4800, v252
	v_cndmask_b32_e64 v248, v248, v252, s[100:101]
	v_add_u32_e32 v253, 0x100, v252
	v_cndmask_b32_e64 v251, v251, v253, s[100:101]
	v_and_b32_e32 v252, 1, v255
	v_lshlrev_b32_e32 v252, 8, v252
	v_add_u32_e32 v252, 0x800, v252
	v_cndmask_b32_e64 v249, v249, v252, s[100:101]
	v_lshrrev_b32_e32 v252, 6, v175
	v_lshlrev_b32_e32 v252, 5, v252
	v_bfe_u32 v253, v175, 4, 2
	v_add3_u32 v247, v247, v252, v253
	v_mul_u32_u24_e32 v247, 0x5800, v247
	v_add3_u32 v247, v247, v248, v249
	v_and_b32_e32 v252, 15, v175
	v_add_u32_e32 v248, 0, v253
	v_xor_b32_e32 v248, v252, v248
	v_lshlrev_b32_e32 v248, 4, v248
	v_add_u32_e32 v249, 4, v253
	v_xor_b32_e32 v249, v252, v249
	v_lshlrev_b32_e32 v249, 4, v249
	v_add_u32_e32 v250, 8, v253
	v_xor_b32_e32 v250, v252, v250
	v_lshlrev_b32_e32 v250, 4, v250
	v_add_u32_e32 v251, 12, v253
	v_xor_b32_e32 v251, v252, v251
	v_lshlrev_b32_e32 v251, 4, v251
	v_readfirstlane_b32 s98, v175
	s_add_u32 s100, s38, 0xba00000
	s_addc_u32 s101, s39, 0
	s_lshr_b32 s98, s98, 6
	s_lshl_b32 s98, s98, 13
	s_add_i32 s98, s98, 0x10000
	v_add_u32_e32 v254, v247, v248
	v_mov_b32_e32 v255, 0
	v_lshl_add_u64 v[254:255], s[100:101], 0, v[254:255]
	s_add_i32 m0, s98, 0x0
	v_add_u32_e32 v247, 0x16000, v247
	global_load_lds_dwordx4 v[254:255], off
	v_add_u32_e32 v254, v247, v249
	v_mov_b32_e32 v255, 0
	v_lshl_add_u64 v[254:255], s[100:101], 0, v[254:255]
	s_add_i32 m0, s98, 0x400
	v_add_u32_e32 v247, 0x16000, v247
	global_load_lds_dwordx4 v[254:255], off
	v_add_u32_e32 v254, v247, v250
	v_mov_b32_e32 v255, 0
	v_lshl_add_u64 v[254:255], s[100:101], 0, v[254:255]
	s_add_i32 m0, s98, 0x800
	v_add_u32_e32 v247, 0x16000, v247
	global_load_lds_dwordx4 v[254:255], off
	v_add_u32_e32 v254, v247, v251
	v_mov_b32_e32 v255, 0
	v_lshl_add_u64 v[254:255], s[100:101], 0, v[254:255]
	s_add_i32 m0, s98, 0xc00
	v_add_u32_e32 v247, 0x16000, v247
	global_load_lds_dwordx4 v[254:255], off
	v_add_u32_e32 v254, v247, v248
	v_mov_b32_e32 v255, 0
	v_lshl_add_u64 v[254:255], s[100:101], 0, v[254:255]
	s_add_i32 m0, s98, 0x1000
	v_add_u32_e32 v247, 0x16000, v247
	global_load_lds_dwordx4 v[254:255], off
	v_add_u32_e32 v254, v247, v249
	v_mov_b32_e32 v255, 0
	v_lshl_add_u64 v[254:255], s[100:101], 0, v[254:255]
	s_add_i32 m0, s98, 0x1400
	v_add_u32_e32 v247, 0x16000, v247
	global_load_lds_dwordx4 v[254:255], off
	v_add_u32_e32 v254, v247, v250
	v_mov_b32_e32 v255, 0
	v_lshl_add_u64 v[254:255], s[100:101], 0, v[254:255]
	s_add_i32 m0, s98, 0x1800
	v_add_u32_e32 v247, 0x16000, v247
	global_load_lds_dwordx4 v[254:255], off
	v_add_u32_e32 v254, v247, v251
	v_mov_b32_e32 v255, 0
	v_lshl_add_u64 v[254:255], s[100:101], 0, v[254:255]
	s_add_i32 m0, s98, 0x1c00
	s_nop 0
	global_load_lds_dwordx4 v[254:255], off
	s_branch .Lzd_entry_2

.Lzd_entry_2:
	s_add_i32 s58, s59, 1
	s_cmp_ge_u32 s58, s56
	s_barrier
	s_cbranch_scc1 .LBB0_459
	s_cmp_lt_u32 s59, 3
	s_cselect_b32 s0, s20, 0xffffff00
	s_add_i32 s0, s0, s57
	s_add_i32 s0, s0, 64
	s_ashr_i32 s1, s0, 31
	s_add_i32 s2, s55, 0x4000
	s_and_b32 s52, s2, 0x4000
	v_lshl_add_u64 v[2:3], s[0:1], 0, v[158:159]
	v_mad_u64_u32 v[4:5], s[2:3], v2, s62, v[162:163]
	s_add_i32 s52, s52, 0
	v_mad_i32_i24 v5, v3, s62, v5
	s_add_i32 s53, s52, s91
	v_lshl_add_u64 v[4:5], v[4:5], 0, s[24:25]
	s_mov_b32 m0, s53
	s_nop 0
	global_load_lds_dwordx4 v[4:5], off
	v_mad_u64_u32 v[4:5], s[2:3], v2, s62, v[164:165]
	v_mad_i32_i24 v5, v3, s62, v5
	s_add_i32 m0, s53, 0x8000
	v_lshl_add_u64 v[2:3], s[0:1], 0, v[160:161]
	global_load_lds_dwordx4 v[4:5], off
	v_mad_u64_u32 v[4:5], s[0:1], v2, s62, v[166:167]
	v_mad_i32_i24 v5, v3, s62, v5
	s_add_i32 s2, s52, s92
	v_lshl_add_u64 v[4:5], v[4:5], 0, s[24:25]
	s_mov_b32 m0, s2
	s_nop 0
	global_load_lds_dwordx4 v[4:5], off
	v_mad_u64_u32 v[4:5], s[0:1], v2, s62, v[168:169]
	v_mad_i32_i24 v5, v3, s62, v5
	s_add_i32 m0, s2, 0x8000
	s_nop 0
	global_load_lds_dwordx4 v[4:5], off

.LBB0_471:
	s_add_i32 s0, s89, 0xfffffb80
	s_lshr_b32 s20, s0, 6
	s_lshl_b32 s53, s89, 7
	s_lshl_b64 s[2:3], s[20:21], 11
	s_and_b32 s0, s53, 0x700
	v_mov_b32_e32 v203, v175
	s_or_b32 s2, s2, s0
	s_mul_hi_u32 s1, s2, 0x5800
	v_readfirstlane_b32 s57, v203
	s_mul_i32 s52, s3, 0x5800
	s_ashr_i32 s56, s57, 6
	s_mul_i32 s0, s2, 0x5800
	s_add_i32 s1, s1, s52
	s_add_u32 s0, s6, s0
	s_addc_u32 s1, s7, s1
	s_lshl_b32 s52, s89, 4
	s_and_b32 s52, s52, 0x300
	s_lshl_b32 s58, s52, 1
	s_add_u32 s0, s0, s58
	s_addc_u32 s1, s1, 0
	s_add_u32 s54, s0, 0x4800
	v_and_b32_e32 v204, 31, v203
	s_addc_u32 s55, s1, 0
	s_lshl_b32 s59, s56, 5
	s_lshl_b64 s[0:1], s[20:21], 20
	s_and_b32 s20, s53, 0x80
	v_or_b32_e32 v0, s59, v204
	v_mov_b64_e32 v[2:3], s[54:55]
	s_lshl_b32 s53, s56, 13
	v_mad_i64_i32 v[2:3], s[54:55], v0, s62, v[2:3]
	s_add_i32 s60, s53, 0
	s_add_i32 s53, s60, 0x10000
	s_ashr_i32 s55, s59, 31
	s_add_u32 s54, s2, s59
	s_addc_u32 s55, s3, s55
	s_mul_i32 s2, s55, 0x5800
	s_mul_hi_u32 s3, s54, 0x5800
	s_add_i32 s3, s3, s2
	s_mul_i32 s2, s54, 0x5800
	s_add_u32 s2, s6, s2
	s_addc_u32 s3, s7, s3
	s_add_u32 s2, s2, s58
	v_bfe_u32 v18, v203, 5, 1
	s_addc_u32 s3, s3, 0
	s_lshl_b32 s58, s20, 1
	v_lshlrev_b32_e32 v0, 4, v18
	s_add_u32 s2, s2, s58
	v_lshl_add_u64 v[2:3], v[2:3], 0, v[0:1]
	s_addc_u32 s3, s3, 0
	v_bfe_u32 v169, v203, 4, 2
	global_load_dwordx4 v[98:101], v[2:3], off
	global_load_dwordx4 v[102:105], v[2:3], off offset:32
	global_load_dwordx4 v[106:109], v[2:3], off offset:64
	global_load_dwordx4 v[110:113], v[2:3], off offset:96
	global_load_dwordx4 v[114:117], v[2:3], off offset:128
	global_load_dwordx4 v[118:121], v[2:3], off offset:160
	global_load_dwordx4 v[122:125], v[2:3], off offset:192
	global_load_dwordx4 v[126:129], v[2:3], off offset:224
	global_load_dwordx4 v[130:133], v[2:3], off offset:256
	global_load_dwordx4 v[134:137], v[2:3], off offset:288
	global_load_dwordx4 v[138:141], v[2:3], off offset:320
	global_load_dwordx4 v[142:145], v[2:3], off offset:352
	global_load_dwordx4 v[146:149], v[2:3], off offset:384
	global_load_dwordx4 v[150:153], v[2:3], off offset:416
	global_load_dwordx4 v[154:157], v[2:3], off offset:448
	global_load_dwordx4 v[158:161], v[2:3], off offset:480
	s_add_u32 s2, s2, 0x5000
	v_mul_u32_u24_e32 v2, 0x2c00, v169
	s_addc_u32 s3, s3, 0
	v_xor_b32_e32 v6, v169, v203
	v_lshlrev_b32_e32 v2, 1, v2
	v_mov_b32_e32 v3, v1
	v_lshl_add_u64 v[4:5], s[2:3], 0, v[2:3]
	v_lshlrev_b32_e32 v3, 3, v6
	v_and_b32_e32 v172, 0x78, v3
	v_lshlrev_b32_e32 v6, 1, v172
	v_mov_b32_e32 v7, v1
	v_bitop3_b32 v3, v169, v203, 4 bitop3:0x36
	v_lshl_add_u64 v[4:5], v[4:5], 0, v[6:7]
	s_mov_b32 m0, s53
	v_lshlrev_b32_e32 v3, 3, v3
	s_nop 0
	v_add_u32_e32 v4, 0x16000, v2
	v_mov_b32_e32 v5, v1
	v_and_b32_e32 v162, 0x78, v3
	v_lshl_add_u64 v[4:5], s[2:3], 0, v[4:5]
	v_lshlrev_b32_e32 v8, 1, v162
	v_mov_b32_e32 v9, v1
	v_bitop3_b32 v3, v169, v203, 8 bitop3:0x36
	v_lshl_add_u64 v[4:5], v[4:5], 0, v[8:9]
	s_add_i32 m0, s60, 0x10400
	v_lshlrev_b32_e32 v3, 3, v3
	s_nop 0
	v_add_u32_e32 v4, 0x2c000, v2
	v_mov_b32_e32 v5, v1
	v_and_b32_e32 v164, 0x78, v3
	v_lshl_add_u64 v[4:5], s[2:3], 0, v[4:5]
	v_lshlrev_b32_e32 v8, 1, v164
	v_bitop3_b32 v3, v169, v203, 12 bitop3:0x36
	v_lshl_add_u64 v[4:5], v[4:5], 0, v[8:9]
	s_add_i32 m0, s60, 0x10800
	v_lshlrev_b32_e32 v3, 3, v3
	s_nop 0
	v_add_u32_e32 v4, 0x42000, v2
	v_mov_b32_e32 v5, v1
	v_and_b32_e32 v166, 0x78, v3
	v_lshl_add_u64 v[4:5], s[2:3], 0, v[4:5]
	v_lshlrev_b32_e32 v8, 1, v166
	v_lshl_add_u64 v[4:5], v[4:5], 0, v[8:9]
	s_add_i32 m0, s60, 0x10c00
	v_bitop3_b32 v3, v169, v203, 20 bitop3:0x36
	s_nop 0
	v_add_u32_e32 v4, 0x58000, v2
	v_mov_b32_e32 v5, v1
	v_lshl_add_u64 v[4:5], s[2:3], 0, v[4:5]
	v_lshl_add_u64 v[4:5], v[4:5], 0, v[6:7]
	s_add_i32 m0, s60, 0x11000
	v_lshlrev_b32_e32 v3, 3, v3
	s_nop 0
	v_add_u32_e32 v4, 0x6e000, v2
	v_mov_b32_e32 v5, v1
	v_and_b32_e32 v168, 0x78, v3
	v_lshl_add_u64 v[4:5], s[2:3], 0, v[4:5]
	v_lshlrev_b32_e32 v6, 1, v168
	v_bitop3_b32 v3, v169, v203, 24 bitop3:0x36
	v_lshl_add_u64 v[4:5], v[4:5], 0, v[6:7]
	s_add_i32 m0, s60, 0x11400
	v_lshlrev_b32_e32 v3, 3, v3
	s_nop 0
	v_add_u32_e32 v4, 0x84000, v2
	v_mov_b32_e32 v5, v1
	v_and_b32_e32 v170, 0x78, v3
	v_lshl_add_u64 v[4:5], s[2:3], 0, v[4:5]
	v_lshlrev_b32_e32 v6, 1, v170
	v_lshl_add_u64 v[4:5], v[4:5], 0, v[6:7]
	s_add_i32 m0, s60, 0x11800
	v_add_u32_e32 v2, 0x9a000, v2
	s_nop 0
	v_bitop3_b32 v4, v169, v203, 28 bitop3:0x36
	v_lshlrev_b32_e32 v4, 3, v4
	v_mov_b32_e32 v3, v1
	v_and_b32_e32 v174, 0x78, v4
	v_lshl_add_u64 v[2:3], s[2:3], 0, v[2:3]
	v_lshlrev_b32_e32 v4, 1, v174
	v_mov_b32_e32 v5, v1
	v_lshl_add_u64 v[2:3], v[2:3], 0, v[4:5]
	s_add_i32 m0, s60, 0x11c00
	v_or_b32_e32 v29, 0x60, v204
	s_nop 0
	v_or_b32_e32 v43, 32, v204
	v_lshrrev_b32_e32 v30, 3, v29
	v_bfe_u32 v36, v203, 3, 2
	v_lshrrev_b32_e32 v43, 3, v43
	v_lshlrev_b32_e32 v205, 3, v18
	v_bitop3_b32 v31, v30, v18, 7 bitop3:0x6c
	v_xor_b32_e32 v37, v18, v36
	v_or_b32_e32 v38, 2, v18
	v_bitop3_b32 v39, v18, v36, 2 bitop3:0x36
	v_or_b32_e32 v40, 4, v18
	v_bitop3_b32 v41, v18, v36, 4 bitop3:0x36
	v_or_b32_e32 v42, 6, v18
	v_bitop3_b32 v36, v18, v36, 6 bitop3:0x36
	v_xor_b32_e32 v44, v43, v18
	v_bitop3_b32 v45, v18, v43, 2 bitop3:0x36
	v_bitop3_b32 v46, v18, v43, 4 bitop3:0x36
	v_bitop3_b32 v18, v18, v43, 6 bitop3:0x36
	v_add_u32_e32 v7, 0x200, v203
	v_add_u32_e32 v11, 0x400, v203
	v_add_u32_e32 v15, 0x600, v203
	v_lshlrev_b32_e32 v43, 4, v18
	v_bitop3_b32 v18, v30, v38, 7 bitop3:0x6c
	s_ashr_i32 s2, s57, 4
	v_ashrrev_i32_e32 v2, 31, v203
	v_ashrrev_i32_e32 v6, 31, v7
	v_ashrrev_i32_e32 v10, 31, v11
	v_ashrrev_i32_e32 v14, 31, v15
	v_lshlrev_b32_e32 v38, 4, v18
	v_bitop3_b32 v18, v30, v40, 7 bitop3:0x6c
	v_bfe_u32 v19, v203, 3, 3
	s_and_b32 s57, s2, 0x7ffffff8
	v_lshrrev_b32_e32 v2, 27, v2
	v_lshrrev_b32_e32 v6, 27, v6
	v_lshrrev_b32_e32 v10, 27, v10
	v_lshrrev_b32_e32 v14, 27, v14
	v_lshlrev_b32_e32 v40, 4, v18
	v_bitop3_b32 v18, v30, v42, 7 bitop3:0x6c
	s_lshl_b32 s3, s56, 3
	v_and_b32_e32 v20, 7, v203
	v_or_b32_e32 v21, s57, v19
	v_add_u32_e32 v3, v203, v2
	v_add_u32_e32 v8, v7, v6
	v_add_u32_e32 v12, v11, v10
	v_add_u32_e32 v16, v15, v14
	v_lshrrev_b32_e32 v27, 1, v203
	v_lshlrev_b32_e32 v30, 4, v18
	s_lshl_b32 s2, s2, 1
	v_lshlrev_b32_e32 v18, 1, v19
	v_and_or_b32 v22, s3, 8, v20
	v_ashrrev_i32_e32 v2, 5, v3
	v_and_b32_e32 v3, 0xffffffe0, v3
	v_ashrrev_i32_e32 v6, 5, v8
	v_and_b32_e32 v8, 0xffffffe0, v8
	v_ashrrev_i32_e32 v10, 5, v12
	v_and_b32_e32 v12, 0xffffffe0, v12
	v_ashrrev_i32_e32 v14, 5, v16
	v_and_b32_e32 v16, 0xffffffe0, v16
	v_lshlrev_b32_e32 v21, 1, v21
	v_and_b32_e32 v27, 8, v27
	s_mov_b32 s3, 0x7ffffff0
	v_and_or_b32 v18, s2, -16, v18
	v_sub_u32_e32 v23, v203, v3
	v_ashrrev_i32_e32 v3, 31, v2
	v_sub_u32_e32 v24, v7, v8
	v_ashrrev_i32_e32 v7, 31, v6
	v_sub_u32_e32 v25, v11, v12
	v_ashrrev_i32_e32 v11, 31, v10
	v_sub_u32_e32 v26, v15, v16
	v_ashrrev_i32_e32 v15, 31, v14
	v_and_or_b32 v27, v21, s3, v27
	v_and_b32_e32 v28, 4, v19
	v_ashrrev_i32_e32 v19, 31, v18
	v_lshrrev_b32_e32 v27, 3, v27
	v_mul_lo_u32 v32, v2, s87
	v_mul_lo_u32 v33, v6, s87
	v_mul_lo_u32 v34, v10, s87
	v_mul_lo_u32 v35, v14, s87
	v_lshlrev_b64 v[18:19], 12, v[18:19]
	s_lshl_b32 s2, s89, 5
	s_lshl_b32 s56, s56, 7
	v_lshlrev_b64 v[14:15], 12, v[14:15]
	v_lshlrev_b64 v[10:11], 12, v[10:11]
	v_lshlrev_b64 v[6:7], 12, v[6:7]
	v_lshlrev_b64 v[2:3], 12, v[2:3]
	v_lshlrev_b32_e32 v4, 3, v23
	v_lshlrev_b32_e32 v8, 3, v24
	v_lshlrev_b32_e32 v12, 3, v25
	v_lshlrev_b32_e32 v16, 3, v26
	v_bitop3_b32 v27, v27, v203, 7 bitop3:0x78
	v_lshl_add_u64 v[18:19], s[0:1], 0, v[18:19]
	s_and_b32 s2, s2, 0x600
	s_and_b32 s3, s89, 1
	s_and_b32 s56, s56, 0x80
	v_lshl_add_u64 v[14:15], s[0:1], 0, v[14:15]
	v_lshl_add_u64 v[10:11], s[0:1], 0, v[10:11]
	v_lshl_add_u64 v[6:7], s[0:1], 0, v[6:7]
	v_lshl_add_u64 v[2:3], s[0:1], 0, v[2:3]
	v_ashrrev_i32_e32 v5, 31, v4
	v_ashrrev_i32_e32 v9, 31, v8
	v_ashrrev_i32_e32 v13, 31, v12
	v_ashrrev_i32_e32 v17, 31, v16
	v_lshlrev_b32_e32 v27, 4, v27
	v_and_or_b32 v21, v21, 2, v28
	v_mul_u32_u24_e32 v22, 0x480, v22
	v_or_b32_e32 v18, s2, v18
	s_lshl_b32 s3, s3, 8
	v_lshl_or_b32 v20, v20, 4, s56
	v_or_b32_e32 v14, s2, v14
	v_or_b32_e32 v10, s2, v10
	v_or_b32_e32 v6, s2, v6
	v_or_b32_e32 v2, s2, v2
	v_lshlrev_b32_e32 v21, 1, v21
	v_mad_u32_u24 v28, v204, s87, 0
	v_lshlrev_b32_e32 v31, 4, v31
	v_mad_u32_u24 v29, v29, s73, 0
	v_add_u32_e32 v32, 0, v32
	v_lshlrev_b32_e32 v23, 4, v23
	v_add_u32_e32 v33, 0, v33
	v_lshlrev_b32_e32 v24, 4, v24
	v_add_u32_e32 v34, 0, v34
	v_lshlrev_b32_e32 v25, 4, v25
	v_add_u32_e32 v35, 0, v35
	v_lshlrev_b32_e32 v26, 4, v26
	v_add3_u32 v22, 0, v22, v27
	v_mad_u32_u24 v27, v204, s73, 0
	v_lshlrev_b32_e32 v37, 4, v37
	v_lshlrev_b32_e32 v39, 4, v39
	v_lshlrev_b32_e32 v41, 4, v41
	v_lshlrev_b32_e32 v36, 4, v36
	v_lshlrev_b32_e32 v44, 4, v44
	v_lshlrev_b32_e32 v45, 4, v45
	v_lshlrev_b32_e32 v46, 4, v46
	v_or3_b32 v18, v18, s3, v20
	v_lshl_add_u64 v[14:15], v[16:17], 1, v[14:15]
	v_lshl_add_u64 v[10:11], v[12:13], 1, v[10:11]
	v_lshl_add_u64 v[6:7], v[8:9], 1, v[6:7]
	v_lshl_add_u64 v[2:3], v[4:5], 1, v[2:3]
	v_mov_b32_e32 v50, v1
	v_mov_b32_e32 v51, v1
	v_lshl_add_u64 v[176:177], s[30:31], 0, v[18:19]
	v_lshl_add_u64 v[178:179], s[10:11], 0, v[14:15]
	v_lshl_add_u64 v[180:181], s[10:11], 0, v[10:11]
	v_lshl_add_u64 v[182:183], s[10:11], 0, v[6:7]
	v_lshl_add_u64 v[184:185], s[10:11], 0, v[2:3]
	v_mov_b32_e32 v52, v1
	v_mov_b32_e32 v53, v1
	v_mov_b32_e32 v54, v1
	v_mov_b32_e32 v55, v1
	v_mov_b32_e32 v56, v1
	v_mov_b32_e32 v57, v1
	v_mov_b32_e32 v58, v1
	v_mov_b32_e32 v59, v1
	v_mov_b32_e32 v60, v1
	v_mov_b32_e32 v61, v1
	v_mov_b32_e32 v62, v1
	v_mov_b32_e32 v63, v1
	v_mov_b32_e32 v64, v1
	v_mov_b32_e32 v65, v1
	v_add_u32_e32 v206, v32, v23
	v_add_u32_e32 v207, v33, v24
	v_add_u32_e32 v208, v34, v25
	v_add_u32_e32 v209, v35, v26
	v_add_u32_e32 v210, v22, v21
	v_add_u32_e32 v211, v28, v0
	v_add_u32_e32 v212, v27, v37
	v_add_u32_e32 v213, v27, v39
	v_add_u32_e32 v214, v27, v41
	v_add_u32_e32 v215, v27, v36
	v_add_u32_e32 v216, v27, v44
	v_add_u32_e32 v217, v27, v45
	v_add_u32_e32 v218, v27, v46
	v_add_u32_e32 v219, v27, v43
	v_add_u32_e32 v220, v29, v31
	v_add_u32_e32 v222, v29, v38
	v_add_u32_e32 v223, v29, v40
	v_add_u32_e32 v224, v29, v30
	v_mov_b64_e32 v[34:35], v[50:51]
	v_mov_b64_e32 v[18:19], v[50:51]
	v_mov_b64_e32 v[2:3], v[50:51]
	v_or_b32_e32 v163, 4, v169
	v_or_b32_e32 v165, 8, v169
	v_or_b32_e32 v167, 12, v169
	v_or_b32_e32 v201, 20, v169
	v_or_b32_e32 v200, 24, v169
	v_or_b32_e32 v202, 28, v169
	v_mov_b32_e32 v221, 0
	v_mov_b32_e32 v225, 0xf149f2ca
	s_mov_b64 s[0:1], 0
	v_mov_b64_e32 v[36:37], v[52:53]
	v_mov_b64_e32 v[38:39], v[54:55]
	v_mov_b64_e32 v[40:41], v[56:57]
	v_mov_b64_e32 v[42:43], v[58:59]
	v_mov_b64_e32 v[44:45], v[60:61]
	v_mov_b64_e32 v[46:47], v[62:63]
	v_mov_b64_e32 v[48:49], v[64:65]
	v_mov_b64_e32 v[20:21], v[52:53]
	v_mov_b64_e32 v[22:23], v[54:55]
	v_mov_b64_e32 v[24:25], v[56:57]
	v_mov_b64_e32 v[26:27], v[58:59]
	v_mov_b64_e32 v[28:29], v[60:61]
	v_mov_b64_e32 v[30:31], v[62:63]
	v_mov_b64_e32 v[32:33], v[64:65]
	v_mov_b64_e32 v[4:5], v[52:53]
	v_mov_b64_e32 v[6:7], v[54:55]
	v_mov_b64_e32 v[8:9], v[56:57]
	v_mov_b64_e32 v[10:11], v[58:59]
	v_mov_b64_e32 v[12:13], v[60:61]
	v_mov_b64_e32 v[14:15], v[62:63]
	v_mov_b64_e32 v[16:17], v[64:65]
.LBB0_472:
	v_lshl_add_u64 v[86:87], v[176:177], 0, s[0:1]
	s_mov_b32 s2, 0x5000000
	v_add_co_u32_e32 v82, vcc, s2, v86
	s_mov_b32 s2, 0x5001000
	s_nop 0
	v_addc_co_u32_e32 v83, vcc, 0, v87, vcc
	v_lshl_add_u64 v[66:67], v[184:185], 0, s[0:1]
	v_lshl_add_u64 v[70:71], v[182:183], 0, s[0:1]
	v_lshl_add_u64 v[74:75], v[180:181], 0, s[0:1]
	v_lshl_add_u64 v[78:79], v[178:179], 0, s[0:1]
	v_add_co_u32_e32 v86, vcc, s2, v86
	global_load_dwordx4 v[66:69], v[66:67], off
	s_nop 0
	global_load_dwordx4 v[70:73], v[70:71], off
	s_nop 0
	global_load_dwordx4 v[74:77], v[74:75], off
	s_nop 0
	global_load_dwordx4 v[78:81], v[78:79], off
	v_addc_co_u32_e32 v87, vcc, 0, v87, vcc
	global_load_dwordx4 v[82:85], v[82:83], off offset:2048
	v_add_u32_e32 v0, 0x9000, v210
	global_load_dwordx4 v[86:89], v[86:87], off offset:2048
	s_waitcnt vmcnt(0) lgkmcnt(0)
	s_barrier
	s_cmp_lg_u32 s0, 0
	s_cbranch_scc1 .Lzd_skip_m
	ds_read_b32 v246, v173
	s_waitcnt lgkmcnt(0)
	v_cmp_gt_u32_e32 vcc, 0x180, v246
	s_nop 1
	v_cndmask_b32_e64 v252, 0, 1, vcc
	v_cmp_gt_u32_e32 vcc, 0xc0, v246
	s_nop 1
	v_cndmask_b32_e64 v253, 0, 1, vcc
	v_mul_u32_u24_e32 v255, 0x5c0, v252
	v_mul_u32_u24_e32 v247, 0xc0, v253
	v_add_u32_e32 v255, v255, v247
	v_sub_u32_e32 v255, 0x680, v255
	v_sub_u32_e32 v255, v246, v255
	v_add_u32_e32 v252, v252, v253
	v_mad_u32_u24 v252, v252, 3, 1
	v_lshrrev_b32_e32 v253, 6, v255
	v_sub_u32_e32 v252, v252, v253
	v_bfe_u32 v247, v255, 3, 3
	v_lshlrev_b32_e32 v247, 11, v247
	v_lshl_add_u32 v247, v252, 8, v247
	v_and_b32_e32 v253, 7, v255
	v_lshlrev_b32_e32 v248, 8, v253
	v_mov_b32_e32 v249, 0x1800
	v_mov_b32_e32 v250, v247
	v_add_u32_e32 v251, 0x800, v248
	v_subrev_u32_e32 v255, 0x180, v246
	v_cmp_gt_u32_e32 vcc, 0x300, v255
	s_nop 3
	s_mov_b64 s[98:99], vcc
	v_bfe_u32 v246, v255, 5, 3
	v_lshlrev_b32_e32 v246, 11, v246
	v_and_b32_e32 v253, 7, v255
	v_lshl_add_u32 v252, v253, 8, v246
	v_cndmask_b32_e64 v247, v247, v252, s[98:99]
	v_lshlrev_b32_e32 v252, 8, v253
	v_and_b32_e32 v253, 0xfffffe00, v252
	v_cmp_le_u32_e32 vcc, 0x200, v255
	s_nop 1
	v_cndmask_b32_e32 v253, v253, v252, vcc
	v_cmp_le_u32_e32 vcc, 0x100, v255
	s_nop 1
	v_cndmask_b32_e64 v253, 0, v253, vcc
	v_subrev_u32_e32 v252, 0x80, v252
	v_max_i32_e32 v252, v252, v253
	v_add_u32_e32 v252, v252, v246
	v_cndmask_b32_e64 v250, v250, v252, s[98:99]
	v_lshrrev_b32_e32 v252, 8, v255
	v_bfe_u32 v253, v255, 3, 2
	v_lshl_add_u32 v252, v252, 2, v253
	v_lshlrev_b32_e32 v252, 8, v252
	v_add_u32_e32 v253, 0x2000, v252
	v_cndmask_b32_e64 v248, v248, v253, s[98:99]
	v_add_u32_e32 v253, 0x2c00, v252
	v_cndmask_b32_e64 v251, v251, v253, s[98:99]
	v_cndmask_b32_e64 v249, v249, 0, s[98:99]
	v_subrev_u32_e32 v255, 0x300, v255
	v_cmp_gt_u32_e32 vcc, 0x200, v255
	s_nop 3
	s_mov_b64 s[100:101], vcc
	v_lshrrev_b32_e32 v252, 6, v255
	v_lshlrev_b32_e32 v252, 11, v252
	v_bfe_u32 v253, v255, 1, 3
	v_lshl_add_u32 v252, v253, 8, v252
	v_cndmask_b32_e64 v247, v247, v252, s[100:101]
	v_cndmask_b32_e64 v250, v250, v252, s[100:101]
	v_bfe_u32 v252, v255, 4, 2
	v_lshlrev_b32_e32 v252, 9, v252
	v_add_u32_e32 v252, 0x4800, v252
	v_cndmask_b32_e64 v248, v248, v252, s[100:101]
	v_add_u32_e32 v253, 0x100, v252
	v_cndmask_b32_e64 v251, v251, v253, s[100:101]
	v_and_b32_e32 v252, 1, v255
	v_lshlrev_b32_e32 v252, 8, v252
	v_add_u32_e32 v252, 0x800, v252
	v_cndmask_b32_e64 v249, v249, v252, s[100:101]
	v_lshrrev_b32_e32 v252, 6, v175
	v_lshlrev_b32_e32 v252, 5, v252
	v_bfe_u32 v253, v175, 4, 2
	v_add3_u32 v247, v247, v252, v253
	v_mul_u32_u24_e32 v247, 0x5800, v247
	v_add3_u32 v247, v247, v248, v249
	v_and_b32_e32 v252, 15, v175
	v_add_u32_e32 v248, 0, v253
	v_xor_b32_e32 v248, v252, v248
	v_lshlrev_b32_e32 v248, 4, v248
	v_add_u32_e32 v249, 4, v253
	v_xor_b32_e32 v249, v252, v249
	v_lshlrev_b32_e32 v249, 4, v249
	v_add_u32_e32 v250, 8, v253
	v_xor_b32_e32 v250, v252, v250
	v_lshlrev_b32_e32 v250, 4, v250
	v_add_u32_e32 v251, 12, v253
	v_xor_b32_e32 v251, v252, v251
	v_lshlrev_b32_e32 v251, 4, v251
	v_readfirstlane_b32 s98, v175
	s_add_u32 s100, s38, 0xba00000
	s_addc_u32 s101, s39, 0
	s_lshr_b32 s98, s98, 6
	s_lshl_b32 s98, s98, 13
	s_add_i32 s98, s98, 0x10000
	v_add_u32_e32 v254, v247, v248
	v_mov_b32_e32 v255, 0
	v_lshl_add_u64 v[254:255], s[100:101], 0, v[254:255]
	s_add_i32 m0, s98, 0x0
	v_add_u32_e32 v247, 0x16000, v247
	global_load_lds_dwordx4 v[254:255], off
	v_add_u32_e32 v254, v247, v249
	v_mov_b32_e32 v255, 0
	v_lshl_add_u64 v[254:255], s[100:101], 0, v[254:255]
	s_add_i32 m0, s98, 0x400
	v_add_u32_e32 v247, 0x16000, v247
	global_load_lds_dwordx4 v[254:255], off
	v_add_u32_e32 v254, v247, v250
	v_mov_b32_e32 v255, 0
	v_lshl_add_u64 v[254:255], s[100:101], 0, v[254:255]
	s_add_i32 m0, s98, 0x800
	v_add_u32_e32 v247, 0x16000, v247
	global_load_lds_dwordx4 v[254:255], off
	v_add_u32_e32 v254, v247, v251
	v_mov_b32_e32 v255, 0
	v_lshl_add_u64 v[254:255], s[100:101], 0, v[254:255]
	s_add_i32 m0, s98, 0xc00
	v_add_u32_e32 v247, 0x16000, v247
	global_load_lds_dwordx4 v[254:255], off
	v_add_u32_e32 v254, v247, v248
	v_mov_b32_e32 v255, 0
	v_lshl_add_u64 v[254:255], s[100:101], 0, v[254:255]
	s_add_i32 m0, s98, 0x1000
	v_add_u32_e32 v247, 0x16000, v247
	global_load_lds_dwordx4 v[254:255], off
	v_add_u32_e32 v254, v247, v249
	v_mov_b32_e32 v255, 0
	v_lshl_add_u64 v[254:255], s[100:101], 0, v[254:255]
	s_add_i32 m0, s98, 0x1400
	v_add_u32_e32 v247, 0x16000, v247
	global_load_lds_dwordx4 v[254:255], off
	v_add_u32_e32 v254, v247, v250
	v_mov_b32_e32 v255, 0
	v_lshl_add_u64 v[254:255], s[100:101], 0, v[254:255]
	s_add_i32 m0, s98, 0x1800
	v_add_u32_e32 v247, 0x16000, v247
	global_load_lds_dwordx4 v[254:255], off
	v_add_u32_e32 v254, v247, v251
	v_mov_b32_e32 v255, 0
	v_lshl_add_u64 v[254:255], s[100:101], 0, v[254:255]
	s_add_i32 m0, s98, 0x1c00
	s_nop 0
	global_load_lds_dwordx4 v[254:255], off
.Lzd_skip_m:
	ds_write_b128 v206, v[66:69]
	ds_write_b128 v207, v[70:73]
	ds_write_b128 v208, v[74:77]
	ds_write_b128 v209, v[78:81]
	v_and_b32_e32 v66, 0xffff, v82
	v_lshrrev_b32_e32 v67, 16, v82
	v_and_b32_e32 v68, 0xffff, v83
	v_lshrrev_b32_e32 v69, 16, v83
	v_and_b32_e32 v70, 0xffff, v84
	v_lshrrev_b32_e32 v71, 16, v84
	v_and_b32_e32 v72, 0xffff, v85
	v_lshrrev_b32_e32 v73, 16, v85
	v_lshl_or_b32 v66, v86, 16, v66
	v_and_or_b32 v67, v86, s68, v67
	v_lshl_or_b32 v68, v87, 16, v68
	v_and_or_b32 v69, v87, s68, v69
	v_lshl_or_b32 v70, v88, 16, v70
	v_and_or_b32 v71, v88, s68, v71
	v_lshl_or_b32 v72, v89, 16, v72
	v_and_or_b32 v73, v89, s68, v73
	ds_write2_b32 v0, v66, v67 offset1:36
	ds_write2_b32 v0, v68, v69 offset0:72 offset1:108
	ds_write2_b32 v0, v70, v71 offset0:144 offset1:180
	ds_write2_b32 v0, v72, v73 offset0:216 offset1:252
	s_waitcnt lgkmcnt(0)
	s_barrier
	ds_read_b128 v[66:69], v211
	ds_read_b128 v[226:229], v211 offset:32
	s_waitcnt lgkmcnt(1)
	v_mfma_f32_32x32x16_bf16 v[66:81], v[66:69], v[98:101], 0
	ds_read_b128 v[82:85], v211 offset:16896
	ds_read_b128 v[230:233], v211 offset:16928
	v_mov_b32_e32 v0, v225
	s_waitcnt lgkmcnt(1)
	v_mfma_f32_32x32x16_bf16 v[82:97], v[82:85], v[98:101], 0
	v_mfma_f32_32x32x16_bf16 v[66:81], v[226:229], v[102:105], v[66:81]
	s_waitcnt lgkmcnt(0)
	v_mfma_f32_32x32x16_bf16 v[82:97], v[230:233], v[102:105], v[82:97]
	ds_read_b128 v[226:229], v211 offset:64
	ds_read_b128 v[230:233], v211 offset:96
	s_waitcnt lgkmcnt(1)
	v_mfma_f32_32x32x16_bf16 v[66:81], v[226:229], v[106:109], v[66:81]
	ds_read_b128 v[226:229], v211 offset:16960
	ds_read_b128 v[234:237], v211 offset:16992
	s_waitcnt lgkmcnt(2)
	v_mfma_f32_32x32x16_bf16 v[66:81], v[230:233], v[110:113], v[66:81]
	s_waitcnt lgkmcnt(1)
	v_mfma_f32_32x32x16_bf16 v[82:97], v[226:229], v[106:109], v[82:97]
	ds_read_b128 v[226:229], v211 offset:128
	ds_read_b128 v[230:233], v211 offset:160
	s_waitcnt lgkmcnt(1)
	v_mfma_f32_32x32x16_bf16 v[66:81], v[226:229], v[114:117], v[66:81]
	v_mfma_f32_32x32x16_bf16 v[82:97], v[234:237], v[110:113], v[82:97]
	ds_read_b128 v[226:229], v211 offset:17024
	ds_read_b128 v[234:237], v211 offset:17056
	s_waitcnt lgkmcnt(2)
	v_mfma_f32_32x32x16_bf16 v[66:81], v[230:233], v[118:121], v[66:81]
	s_waitcnt lgkmcnt(1)
	v_mfma_f32_32x32x16_bf16 v[82:97], v[226:229], v[114:117], v[82:97]
	ds_read_b128 v[226:229], v211 offset:192
	ds_read_b128 v[230:233], v211 offset:224
	s_waitcnt lgkmcnt(1)
	v_mfma_f32_32x32x16_bf16 v[66:81], v[226:229], v[122:125], v[66:81]
	v_mfma_f32_32x32x16_bf16 v[82:97], v[234:237], v[118:121], v[82:97]
	ds_read_b128 v[226:229], v211 offset:17088
	ds_read_b128 v[234:237], v211 offset:17120
	s_waitcnt lgkmcnt(2)
	v_mfma_f32_32x32x16_bf16 v[66:81], v[230:233], v[126:129], v[66:81]
	s_waitcnt lgkmcnt(1)
	v_mfma_f32_32x32x16_bf16 v[82:97], v[226:229], v[122:125], v[82:97]
	ds_read_b128 v[226:229], v211 offset:256
	ds_read_b128 v[230:233], v211 offset:288
	s_waitcnt lgkmcnt(1)
	v_mfma_f32_32x32x16_bf16 v[66:81], v[226:229], v[130:133], v[66:81]
	v_mfma_f32_32x32x16_bf16 v[82:97], v[234:237], v[126:129], v[82:97]
	ds_read_b128 v[226:229], v211 offset:17152
	ds_read_b128 v[234:237], v211 offset:17184
	s_waitcnt lgkmcnt(2)
	v_mfma_f32_32x32x16_bf16 v[66:81], v[230:233], v[134:137], v[66:81]
	s_waitcnt lgkmcnt(1)
	v_mfma_f32_32x32x16_bf16 v[82:97], v[226:229], v[130:133], v[82:97]
	ds_read_b128 v[226:229], v211 offset:320
	ds_read_b128 v[230:233], v211 offset:352
	s_waitcnt lgkmcnt(1)
	v_mfma_f32_32x32x16_bf16 v[66:81], v[226:229], v[138:141], v[66:81]
	s_waitcnt lgkmcnt(0)
	v_mfma_f32_32x32x16_bf16 v[66:81], v[230:233], v[142:145], v[66:81]
	ds_read_b128 v[226:229], v211 offset:384
	ds_read_b128 v[230:233], v211 offset:416
	s_waitcnt lgkmcnt(1)
	v_mfma_f32_32x32x16_bf16 v[66:81], v[226:229], v[146:149], v[66:81]
	s_waitcnt lgkmcnt(0)
	v_mfma_f32_32x32x16_bf16 v[66:81], v[230:233], v[150:153], v[66:81]
	ds_read_b128 v[226:229], v211 offset:448
	ds_read_b128 v[230:233], v211 offset:480
	s_waitcnt lgkmcnt(1)
	v_mfma_f32_32x32x16_bf16 v[66:81], v[226:229], v[154:157], v[66:81]
	v_mfma_f32_32x32x16_bf16 v[82:97], v[234:237], v[134:137], v[82:97]
	s_waitcnt lgkmcnt(0)
	v_mfma_f32_32x32x16_bf16 v[66:81], v[230:233], v[158:161], v[66:81]
	ds_read_b128 v[226:229], v211 offset:17216
	ds_read_b128 v[230:233], v211 offset:17248
	s_waitcnt lgkmcnt(1)
	v_mfma_f32_32x32x16_bf16 v[82:97], v[226:229], v[138:141], v[82:97]
	s_nop 7
	v_max_f32_e32 v186, v67, v67
	v_max_f32_e32 v225, v66, v66
	v_max_f32_e32 v186, v225, v186
	v_max3_f32 v186, v186, v68, v69
	v_max3_f32 v186, v186, v70, v71
	v_max3_f32 v186, v186, v72, v73
	v_max3_f32 v186, v186, v74, v75
	s_waitcnt lgkmcnt(0)
	v_mfma_f32_32x32x16_bf16 v[82:97], v[230:233], v[142:145], v[82:97]
	ds_read_b128 v[226:229], v211 offset:17280
	ds_read_b128 v[230:233], v211 offset:17312
	v_max3_f32 v186, v186, v76, v77
	v_max3_f32 v186, v186, v78, v79
	v_max3_f32 v186, v186, v80, v81
	s_waitcnt lgkmcnt(1)
	v_mfma_f32_32x32x16_bf16 v[82:97], v[226:229], v[146:149], v[82:97]
	ds_read_b128 v[226:229], v211 offset:17344
	s_waitcnt lgkmcnt(1)
	v_mfma_f32_32x32x16_bf16 v[82:97], v[230:233], v[150:153], v[82:97]
	ds_read_b128 v[230:233], v211 offset:17376
	s_waitcnt lgkmcnt(1)
	v_mfma_f32_32x32x16_bf16 v[82:97], v[226:229], v[154:157], v[82:97]
	s_waitcnt lgkmcnt(0)
	v_mfma_f32_32x32x16_bf16 v[82:97], v[230:233], v[158:161], v[82:97]
	s_nop 11
	v_max3_f32 v186, v186, v82, v83
	v_max3_f32 v186, v186, v84, v85
	v_max3_f32 v186, v186, v86, v87
	v_max3_f32 v186, v186, v88, v89
	v_max3_f32 v186, v186, v90, v91
	v_max3_f32 v186, v186, v92, v93
	v_max3_f32 v186, v186, v94, v95
	v_max3_f32 v186, v186, v96, v97
	v_mov_b32_e32 v225, v186
	s_nop 1
	v_permlane32_swap_b32_e32 v186, v225
	v_max3_f32 v225, v0, v186, v225
	v_sub_f32_e32 v0, v0, v225
	v_exp_f32_e32 v186, v0
	s_nop 0
	v_cmp_neq_f32_e32 vcc, 1.0, v186
	s_cbranch_vccz .LBB0_474
	v_pk_mul_f32 v[64:65], v[64:65], v[186:187] op_sel_hi:[1,0]
	v_pk_mul_f32 v[62:63], v[62:63], v[186:187] op_sel_hi:[1,0]
	v_pk_mul_f32 v[60:61], v[60:61], v[186:187] op_sel_hi:[1,0]
	v_pk_mul_f32 v[58:59], v[58:59], v[186:187] op_sel_hi:[1,0]
	v_pk_mul_f32 v[56:57], v[56:57], v[186:187] op_sel_hi:[1,0]
	v_pk_mul_f32 v[54:55], v[54:55], v[186:187] op_sel_hi:[1,0]
	v_pk_mul_f32 v[52:53], v[52:53], v[186:187] op_sel_hi:[1,0]
	v_pk_mul_f32 v[50:51], v[50:51], v[186:187] op_sel_hi:[1,0]
	v_pk_mul_f32 v[48:49], v[48:49], v[186:187] op_sel_hi:[1,0]
	v_pk_mul_f32 v[46:47], v[46:47], v[186:187] op_sel_hi:[1,0]
	v_pk_mul_f32 v[44:45], v[44:45], v[186:187] op_sel_hi:[1,0]
	v_pk_mul_f32 v[42:43], v[42:43], v[186:187] op_sel_hi:[1,0]
	v_pk_mul_f32 v[40:41], v[40:41], v[186:187] op_sel_hi:[1,0]
	v_pk_mul_f32 v[38:39], v[38:39], v[186:187] op_sel_hi:[1,0]
	v_pk_mul_f32 v[36:37], v[36:37], v[186:187] op_sel_hi:[1,0]
	v_pk_mul_f32 v[34:35], v[34:35], v[186:187] op_sel_hi:[1,0]
	v_pk_mul_f32 v[32:33], v[32:33], v[186:187] op_sel_hi:[1,0]
	v_pk_mul_f32 v[30:31], v[30:31], v[186:187] op_sel_hi:[1,0]
	v_pk_mul_f32 v[28:29], v[28:29], v[186:187] op_sel_hi:[1,0]
	v_pk_mul_f32 v[26:27], v[26:27], v[186:187] op_sel_hi:[1,0]
	v_pk_mul_f32 v[24:25], v[24:25], v[186:187] op_sel_hi:[1,0]
	v_pk_mul_f32 v[22:23], v[22:23], v[186:187] op_sel_hi:[1,0]
	v_pk_mul_f32 v[20:21], v[20:21], v[186:187] op_sel_hi:[1,0]
	v_pk_mul_f32 v[18:19], v[18:19], v[186:187] op_sel_hi:[1,0]
	v_pk_mul_f32 v[16:17], v[16:17], v[186:187] op_sel_hi:[1,0]
	v_pk_mul_f32 v[14:15], v[14:15], v[186:187] op_sel_hi:[1,0]
	v_pk_mul_f32 v[12:13], v[12:13], v[186:187] op_sel_hi:[1,0]
	v_pk_mul_f32 v[10:11], v[10:11], v[186:187] op_sel_hi:[1,0]
	v_pk_mul_f32 v[8:9], v[8:9], v[186:187] op_sel_hi:[1,0]
	v_pk_mul_f32 v[6:7], v[6:7], v[186:187] op_sel_hi:[1,0]
	v_pk_mul_f32 v[4:5], v[4:5], v[186:187] op_sel_hi:[1,0]
	v_pk_mul_f32 v[2:3], v[2:3], v[186:187] op_sel_hi:[1,0]
